# v87 plus cross-tile prefetch in the MLP1A/MLP1B hand tiles: the next tile's bias loads and first four K-steps of LDS-DMA are issued before the current tile's epilogue
# baseline (speedup 1.0000x reference)
.Lmain_mlp1b:
	s_mov_b32 s32, 0
	s_mov_b32 s57, 0
	s_nop 1
	v_add_u32_e32 v168, s32, v165
	v_add_u32_e32 v169, s32, v164
	ds_read_b128 v[132:135], v168 offset:16
	ds_read_b128 v[136:139], v168 offset:1040
	ds_read_b128 v[140:143], v168 offset:2064
	ds_read_b128 v[144:147], v168 offset:3088
	ds_read_b128 v[184:187], v169 offset:16
	ds_read_b128 v[188:191], v169 offset:1040
	ds_read_b128 v[192:195], v169 offset:2064
	ds_read_b128 v[196:199], v169 offset:3088
	s_waitcnt lgkmcnt(0)
.Lt_mlp1b:
	v_add_u32_e32 v169, s32, v164
	v_mfma_f32_16x16x32_f16 v[4:7], v[132:135], v[184:187], v[4:7]
	ds_read_b128 v[238:241], v169 offset:4112
	v_mfma_f32_16x16x32_f16 v[8:11], v[136:139], v[184:187], v[8:11]
	ds_read_b128 v[242:245], v169 offset:5136
	v_mfma_f32_16x16x32_f16 v[12:15], v[140:143], v[184:187], v[12:15]
	ds_read_b128 v[246:249], v169 offset:6160
	v_mfma_f32_16x16x32_f16 v[16:19], v[144:147], v[184:187], v[16:19]
	ds_read_b128 v[250:253], v169 offset:7184
	v_mfma_f32_16x16x32_f16 v[20:23], v[132:135], v[188:191], v[20:23]
	v_mfma_f32_16x16x32_f16 v[24:27], v[136:139], v[188:191], v[24:27]
	v_mfma_f32_16x16x32_f16 v[28:31], v[140:143], v[188:191], v[28:31]
	v_mfma_f32_16x16x32_f16 v[32:35], v[144:147], v[188:191], v[32:35]
	v_mfma_f32_16x16x32_f16 v[36:39], v[132:135], v[192:195], v[36:39]
	v_mfma_f32_16x16x32_f16 v[40:43], v[136:139], v[192:195], v[40:43]
	v_mfma_f32_16x16x32_f16 v[44:47], v[140:143], v[192:195], v[44:47]
	v_mfma_f32_16x16x32_f16 v[48:51], v[144:147], v[192:195], v[48:51]
	v_mfma_f32_16x16x32_f16 v[52:55], v[132:135], v[196:199], v[52:55]
	v_mfma_f32_16x16x32_f16 v[56:59], v[136:139], v[196:199], v[56:59]
	v_mfma_f32_16x16x32_f16 v[60:63], v[140:143], v[196:199], v[60:63]
	v_mfma_f32_16x16x32_f16 v[64:67], v[144:147], v[196:199], v[64:67]
	s_waitcnt vmcnt(8) lgkmcnt(0)
	s_barrier
	s_add_i32 s37, s32, 0x8000
	s_cmp_lg_u32 s32, 0x18000
	s_cselect_b32 s37, s37, 0
	v_add_u32_e32 v168, s37, v165
	v_add_u32_e32 v169, s37, v164
	s_add_u32 vcc_lo, s24, s32
	v_mfma_f32_16x16x32_f16 v[68:71], v[132:135], v[238:241], v[68:71]
	ds_read_b128 v[148:151], v168 offset:16
	ds_read_b128 v[184:187], v169 offset:16
	v_mfma_f32_16x16x32_f16 v[72:75], v[136:139], v[238:241], v[72:75]
	ds_read_b128 v[152:155], v168 offset:1040
	ds_read_b128 v[188:191], v169 offset:1040
	v_mfma_f32_16x16x32_f16 v[76:79], v[140:143], v[238:241], v[76:79]
	ds_read_b128 v[156:159], v168 offset:2064
	ds_read_b128 v[192:195], v169 offset:2064
	v_mfma_f32_16x16x32_f16 v[80:83], v[144:147], v[238:241], v[80:83]
	ds_read_b128 v[160:163], v168 offset:3088
	ds_read_b128 v[196:199], v169 offset:3088
	v_mfma_f32_16x16x32_f16 v[84:87], v[132:135], v[242:245], v[84:87]
	v_mfma_f32_16x16x32_f16 v[88:91], v[136:139], v[242:245], v[88:91]
	v_mfma_f32_16x16x32_f16 v[92:95], v[140:143], v[242:245], v[92:95]
	v_mfma_f32_16x16x32_f16 v[96:99], v[144:147], v[242:245], v[96:99]
	v_mfma_f32_16x16x32_f16 v[100:103], v[132:135], v[246:249], v[100:103]
	s_mov_b32 m0, vcc_lo
	s_nop 0
	global_load_lds_dwordx4 v170, s[30:31]
	v_mfma_f32_16x16x32_f16 v[104:107], v[136:139], v[246:249], v[104:107]
	s_add_u32 m0, vcc_lo, 0x400
	s_nop 0
	global_load_lds_dwordx4 v171, s[30:31]
	v_mfma_f32_16x16x32_f16 v[108:111], v[140:143], v[246:249], v[108:111]
	s_add_u32 m0, vcc_lo, 0x4000
	s_nop 0
	global_load_lds_dwordx4 v170, s[52:53]
	v_mfma_f32_16x16x32_f16 v[112:115], v[144:147], v[246:249], v[112:115]
	s_add_u32 m0, vcc_lo, 0x4400
	s_nop 0
	global_load_lds_dwordx4 v171, s[52:53]
	v_mfma_f32_16x16x32_f16 v[116:119], v[132:135], v[250:253], v[116:119]
	v_mfma_f32_16x16x32_f16 v[120:123], v[136:139], v[250:253], v[120:123]
	v_mfma_f32_16x16x32_f16 v[124:127], v[140:143], v[250:253], v[124:127]
	v_mfma_f32_16x16x32_f16 v[128:131], v[144:147], v[250:253], v[128:131]
	s_waitcnt lgkmcnt(0)
	s_mov_b32 s32, s37
	s_add_u32 s30, s30, 64
	s_addc_u32 s31, s31, 0
	s_add_u32 s52, s52, 64
	s_addc_u32 s53, s53, 0
	v_add_u32_e32 v169, s32, v164
	v_mfma_f32_16x16x32_f16 v[4:7], v[148:151], v[184:187], v[4:7]
	ds_read_b128 v[238:241], v169 offset:4112
	v_mfma_f32_16x16x32_f16 v[8:11], v[152:155], v[184:187], v[8:11]
	ds_read_b128 v[242:245], v169 offset:5136
	v_mfma_f32_16x16x32_f16 v[12:15], v[156:159], v[184:187], v[12:15]
	ds_read_b128 v[246:249], v169 offset:6160
	v_mfma_f32_16x16x32_f16 v[16:19], v[160:163], v[184:187], v[16:19]
	ds_read_b128 v[250:253], v169 offset:7184
	v_mfma_f32_16x16x32_f16 v[20:23], v[148:151], v[188:191], v[20:23]
	v_mfma_f32_16x16x32_f16 v[24:27], v[152:155], v[188:191], v[24:27]
	v_mfma_f32_16x16x32_f16 v[28:31], v[156:159], v[188:191], v[28:31]
	v_mfma_f32_16x16x32_f16 v[32:35], v[160:163], v[188:191], v[32:35]
	v_mfma_f32_16x16x32_f16 v[36:39], v[148:151], v[192:195], v[36:39]
	v_mfma_f32_16x16x32_f16 v[40:43], v[152:155], v[192:195], v[40:43]
	v_mfma_f32_16x16x32_f16 v[44:47], v[156:159], v[192:195], v[44:47]
	v_mfma_f32_16x16x32_f16 v[48:51], v[160:163], v[192:195], v[48:51]
	v_mfma_f32_16x16x32_f16 v[52:55], v[148:151], v[196:199], v[52:55]
	v_mfma_f32_16x16x32_f16 v[56:59], v[152:155], v[196:199], v[56:59]
	v_mfma_f32_16x16x32_f16 v[60:63], v[156:159], v[196:199], v[60:63]
	v_mfma_f32_16x16x32_f16 v[64:67], v[160:163], v[196:199], v[64:67]
	s_waitcnt vmcnt(8) lgkmcnt(0)
	s_barrier
	s_add_i32 s37, s32, 0x8000
	s_cmp_lg_u32 s32, 0x18000
	s_cselect_b32 s37, s37, 0
	v_add_u32_e32 v168, s37, v165
	v_add_u32_e32 v169, s37, v164
	s_add_u32 vcc_lo, s24, s32
	v_mfma_f32_16x16x32_f16 v[68:71], v[148:151], v[238:241], v[68:71]
	ds_read_b128 v[132:135], v168 offset:16
	ds_read_b128 v[184:187], v169 offset:16
	v_mfma_f32_16x16x32_f16 v[72:75], v[152:155], v[238:241], v[72:75]
	ds_read_b128 v[136:139], v168 offset:1040
	ds_read_b128 v[188:191], v169 offset:1040
	v_mfma_f32_16x16x32_f16 v[76:79], v[156:159], v[238:241], v[76:79]
	ds_read_b128 v[140:143], v168 offset:2064
	ds_read_b128 v[192:195], v169 offset:2064
	v_mfma_f32_16x16x32_f16 v[80:83], v[160:163], v[238:241], v[80:83]
	ds_read_b128 v[144:147], v168 offset:3088
	ds_read_b128 v[196:199], v169 offset:3088
	v_mfma_f32_16x16x32_f16 v[84:87], v[148:151], v[242:245], v[84:87]
	v_mfma_f32_16x16x32_f16 v[88:91], v[152:155], v[242:245], v[88:91]
	v_mfma_f32_16x16x32_f16 v[92:95], v[156:159], v[242:245], v[92:95]
	v_mfma_f32_16x16x32_f16 v[96:99], v[160:163], v[242:245], v[96:99]
	v_mfma_f32_16x16x32_f16 v[100:103], v[148:151], v[246:249], v[100:103]
	s_mov_b32 m0, vcc_lo
	s_nop 0
	global_load_lds_dwordx4 v170, s[30:31]
	v_mfma_f32_16x16x32_f16 v[104:107], v[152:155], v[246:249], v[104:107]
	s_add_u32 m0, vcc_lo, 0x400
	s_nop 0
	global_load_lds_dwordx4 v171, s[30:31]
	v_mfma_f32_16x16x32_f16 v[108:111], v[156:159], v[246:249], v[108:111]
	s_add_u32 m0, vcc_lo, 0x4000
	s_nop 0
	global_load_lds_dwordx4 v170, s[52:53]
	v_mfma_f32_16x16x32_f16 v[112:115], v[160:163], v[246:249], v[112:115]
	s_add_u32 m0, vcc_lo, 0x4400
	s_nop 0
	global_load_lds_dwordx4 v171, s[52:53]
	v_mfma_f32_16x16x32_f16 v[116:119], v[148:151], v[250:253], v[116:119]
	v_mfma_f32_16x16x32_f16 v[120:123], v[152:155], v[250:253], v[120:123]
	v_mfma_f32_16x16x32_f16 v[124:127], v[156:159], v[250:253], v[124:127]
	v_mfma_f32_16x16x32_f16 v[128:131], v[160:163], v[250:253], v[128:131]
	s_waitcnt lgkmcnt(0)
	s_mov_b32 s32, s37
	s_add_u32 s30, s30, 64
	s_addc_u32 s31, s31, 0
	s_add_u32 s52, s52, 64
	s_addc_u32 s53, s53, 0
	s_add_i32 s57, s57, 2
	s_cmp_lt_u32 s57, 28
	s_cbranch_scc1 .Lt_mlp1b
	v_add_u32_e32 v169, s32, v164
	v_mfma_f32_16x16x32_f16 v[4:7], v[132:135], v[184:187], v[4:7]
	ds_read_b128 v[238:241], v169 offset:4112
	v_mfma_f32_16x16x32_f16 v[8:11], v[136:139], v[184:187], v[8:11]
	ds_read_b128 v[242:245], v169 offset:5136
	v_mfma_f32_16x16x32_f16 v[12:15], v[140:143], v[184:187], v[12:15]
	ds_read_b128 v[246:249], v169 offset:6160
	v_mfma_f32_16x16x32_f16 v[16:19], v[144:147], v[184:187], v[16:19]
	ds_read_b128 v[250:253], v169 offset:7184
	v_mfma_f32_16x16x32_f16 v[20:23], v[132:135], v[188:191], v[20:23]
	v_mfma_f32_16x16x32_f16 v[24:27], v[136:139], v[188:191], v[24:27]
	v_mfma_f32_16x16x32_f16 v[28:31], v[140:143], v[188:191], v[28:31]
	v_mfma_f32_16x16x32_f16 v[32:35], v[144:147], v[188:191], v[32:35]
	v_mfma_f32_16x16x32_f16 v[36:39], v[132:135], v[192:195], v[36:39]
	v_mfma_f32_16x16x32_f16 v[40:43], v[136:139], v[192:195], v[40:43]
	v_mfma_f32_16x16x32_f16 v[44:47], v[140:143], v[192:195], v[44:47]
	v_mfma_f32_16x16x32_f16 v[48:51], v[144:147], v[192:195], v[48:51]
	v_mfma_f32_16x16x32_f16 v[52:55], v[132:135], v[196:199], v[52:55]
	v_mfma_f32_16x16x32_f16 v[56:59], v[136:139], v[196:199], v[56:59]
	v_mfma_f32_16x16x32_f16 v[60:63], v[140:143], v[196:199], v[60:63]
	v_mfma_f32_16x16x32_f16 v[64:67], v[144:147], v[196:199], v[64:67]
	s_waitcnt vmcnt(8) lgkmcnt(0)
	s_barrier
	s_add_i32 s37, s32, 0x8000
	s_cmp_lg_u32 s32, 0x18000
	s_cselect_b32 s37, s37, 0
	v_add_u32_e32 v168, s37, v165
	v_add_u32_e32 v169, s37, v164
	v_mfma_f32_16x16x32_f16 v[68:71], v[132:135], v[238:241], v[68:71]
	ds_read_b128 v[148:151], v168 offset:16
	ds_read_b128 v[184:187], v169 offset:16
	v_mfma_f32_16x16x32_f16 v[72:75], v[136:139], v[238:241], v[72:75]
	ds_read_b128 v[152:155], v168 offset:1040
	ds_read_b128 v[188:191], v169 offset:1040
	v_mfma_f32_16x16x32_f16 v[76:79], v[140:143], v[238:241], v[76:79]
	ds_read_b128 v[156:159], v168 offset:2064
	ds_read_b128 v[192:195], v169 offset:2064
	v_mfma_f32_16x16x32_f16 v[80:83], v[144:147], v[238:241], v[80:83]
	ds_read_b128 v[160:163], v168 offset:3088
	ds_read_b128 v[196:199], v169 offset:3088
	v_mfma_f32_16x16x32_f16 v[84:87], v[132:135], v[242:245], v[84:87]
	v_mfma_f32_16x16x32_f16 v[88:91], v[136:139], v[242:245], v[88:91]
	v_mfma_f32_16x16x32_f16 v[92:95], v[140:143], v[242:245], v[92:95]
	v_mfma_f32_16x16x32_f16 v[96:99], v[144:147], v[242:245], v[96:99]
	v_mfma_f32_16x16x32_f16 v[100:103], v[132:135], v[246:249], v[100:103]
	v_mfma_f32_16x16x32_f16 v[104:107], v[136:139], v[246:249], v[104:107]
	v_mfma_f32_16x16x32_f16 v[108:111], v[140:143], v[246:249], v[108:111]
	v_mfma_f32_16x16x32_f16 v[112:115], v[144:147], v[246:249], v[112:115]
	v_mfma_f32_16x16x32_f16 v[116:119], v[132:135], v[250:253], v[116:119]
	v_mfma_f32_16x16x32_f16 v[120:123], v[136:139], v[250:253], v[120:123]
	v_mfma_f32_16x16x32_f16 v[124:127], v[140:143], v[250:253], v[124:127]
	v_mfma_f32_16x16x32_f16 v[128:131], v[144:147], v[250:253], v[128:131]
	s_waitcnt lgkmcnt(0)
	s_mov_b32 s32, s37
	v_add_u32_e32 v169, s32, v164
	v_mfma_f32_16x16x32_f16 v[4:7], v[148:151], v[184:187], v[4:7]
	ds_read_b128 v[238:241], v169 offset:4112
	v_mfma_f32_16x16x32_f16 v[8:11], v[152:155], v[184:187], v[8:11]
	ds_read_b128 v[242:245], v169 offset:5136
	v_mfma_f32_16x16x32_f16 v[12:15], v[156:159], v[184:187], v[12:15]
	ds_read_b128 v[246:249], v169 offset:6160
	v_mfma_f32_16x16x32_f16 v[16:19], v[160:163], v[184:187], v[16:19]
	ds_read_b128 v[250:253], v169 offset:7184
	v_mfma_f32_16x16x32_f16 v[20:23], v[148:151], v[188:191], v[20:23]
	v_mfma_f32_16x16x32_f16 v[24:27], v[152:155], v[188:191], v[24:27]
	v_mfma_f32_16x16x32_f16 v[28:31], v[156:159], v[188:191], v[28:31]
	v_mfma_f32_16x16x32_f16 v[32:35], v[160:163], v[188:191], v[32:35]
	v_mfma_f32_16x16x32_f16 v[36:39], v[148:151], v[192:195], v[36:39]
	v_mfma_f32_16x16x32_f16 v[40:43], v[152:155], v[192:195], v[40:43]
	v_mfma_f32_16x16x32_f16 v[44:47], v[156:159], v[192:195], v[44:47]
	v_mfma_f32_16x16x32_f16 v[48:51], v[160:163], v[192:195], v[48:51]
	v_mfma_f32_16x16x32_f16 v[52:55], v[148:151], v[196:199], v[52:55]
	v_mfma_f32_16x16x32_f16 v[56:59], v[152:155], v[196:199], v[56:59]
	v_mfma_f32_16x16x32_f16 v[60:63], v[156:159], v[196:199], v[60:63]
	v_mfma_f32_16x16x32_f16 v[64:67], v[160:163], v[196:199], v[64:67]
	s_waitcnt vmcnt(4) lgkmcnt(0)
	s_barrier
	s_add_i32 s37, s32, 0x8000
	s_cmp_lg_u32 s32, 0x18000
	s_cselect_b32 s37, s37, 0
	v_add_u32_e32 v168, s37, v165
	v_add_u32_e32 v169, s37, v164
	v_mfma_f32_16x16x32_f16 v[68:71], v[148:151], v[238:241], v[68:71]
	ds_read_b128 v[132:135], v168 offset:16
	ds_read_b128 v[184:187], v169 offset:16
	v_mfma_f32_16x16x32_f16 v[72:75], v[152:155], v[238:241], v[72:75]
	ds_read_b128 v[136:139], v168 offset:1040
	ds_read_b128 v[188:191], v169 offset:1040
	v_mfma_f32_16x16x32_f16 v[76:79], v[156:159], v[238:241], v[76:79]
	ds_read_b128 v[140:143], v168 offset:2064
	ds_read_b128 v[192:195], v169 offset:2064
	v_mfma_f32_16x16x32_f16 v[80:83], v[160:163], v[238:241], v[80:83]
	ds_read_b128 v[144:147], v168 offset:3088
	ds_read_b128 v[196:199], v169 offset:3088
	v_mfma_f32_16x16x32_f16 v[84:87], v[148:151], v[242:245], v[84:87]
	v_mfma_f32_16x16x32_f16 v[88:91], v[152:155], v[242:245], v[88:91]
	v_mfma_f32_16x16x32_f16 v[92:95], v[156:159], v[242:245], v[92:95]
	v_mfma_f32_16x16x32_f16 v[96:99], v[160:163], v[242:245], v[96:99]
	v_mfma_f32_16x16x32_f16 v[100:103], v[148:151], v[246:249], v[100:103]
	v_mfma_f32_16x16x32_f16 v[104:107], v[152:155], v[246:249], v[104:107]
	v_mfma_f32_16x16x32_f16 v[108:111], v[156:159], v[246:249], v[108:111]
	v_mfma_f32_16x16x32_f16 v[112:115], v[160:163], v[246:249], v[112:115]
	v_mfma_f32_16x16x32_f16 v[116:119], v[148:151], v[250:253], v[116:119]
	v_mfma_f32_16x16x32_f16 v[120:123], v[152:155], v[250:253], v[120:123]
	v_mfma_f32_16x16x32_f16 v[124:127], v[156:159], v[250:253], v[124:127]
	v_mfma_f32_16x16x32_f16 v[128:131], v[160:163], v[250:253], v[128:131]
	s_waitcnt lgkmcnt(0)
	s_mov_b32 s32, s37
	v_add_u32_e32 v169, s32, v164
	v_mfma_f32_16x16x32_f16 v[4:7], v[132:135], v[184:187], v[4:7]
	ds_read_b128 v[238:241], v169 offset:4112
	v_mfma_f32_16x16x32_f16 v[8:11], v[136:139], v[184:187], v[8:11]
	ds_read_b128 v[242:245], v169 offset:5136
	v_mfma_f32_16x16x32_f16 v[12:15], v[140:143], v[184:187], v[12:15]
	ds_read_b128 v[246:249], v169 offset:6160
	v_mfma_f32_16x16x32_f16 v[16:19], v[144:147], v[184:187], v[16:19]
	ds_read_b128 v[250:253], v169 offset:7184
	v_mfma_f32_16x16x32_f16 v[20:23], v[132:135], v[188:191], v[20:23]
	v_mfma_f32_16x16x32_f16 v[24:27], v[136:139], v[188:191], v[24:27]
	v_mfma_f32_16x16x32_f16 v[28:31], v[140:143], v[188:191], v[28:31]
	v_mfma_f32_16x16x32_f16 v[32:35], v[144:147], v[188:191], v[32:35]
	v_mfma_f32_16x16x32_f16 v[36:39], v[132:135], v[192:195], v[36:39]
	v_mfma_f32_16x16x32_f16 v[40:43], v[136:139], v[192:195], v[40:43]
	v_mfma_f32_16x16x32_f16 v[44:47], v[140:143], v[192:195], v[44:47]
	v_mfma_f32_16x16x32_f16 v[48:51], v[144:147], v[192:195], v[48:51]
	v_mfma_f32_16x16x32_f16 v[52:55], v[132:135], v[196:199], v[52:55]
	v_mfma_f32_16x16x32_f16 v[56:59], v[136:139], v[196:199], v[56:59]
	v_mfma_f32_16x16x32_f16 v[60:63], v[140:143], v[196:199], v[60:63]
	v_mfma_f32_16x16x32_f16 v[64:67], v[144:147], v[196:199], v[64:67]
	s_waitcnt vmcnt(0) lgkmcnt(0)
	s_barrier
	s_add_i32 s37, s32, 0x8000
	s_cmp_lg_u32 s32, 0x18000
	s_cselect_b32 s37, s37, 0
	v_add_u32_e32 v168, s37, v165
	v_add_u32_e32 v169, s37, v164
	v_mfma_f32_16x16x32_f16 v[68:71], v[132:135], v[238:241], v[68:71]
	ds_read_b128 v[148:151], v168 offset:16
	ds_read_b128 v[184:187], v169 offset:16
	v_mfma_f32_16x16x32_f16 v[72:75], v[136:139], v[238:241], v[72:75]
	ds_read_b128 v[152:155], v168 offset:1040
	ds_read_b128 v[188:191], v169 offset:1040
	v_mfma_f32_16x16x32_f16 v[76:79], v[140:143], v[238:241], v[76:79]
	ds_read_b128 v[156:159], v168 offset:2064
	ds_read_b128 v[192:195], v169 offset:2064
	v_mfma_f32_16x16x32_f16 v[80:83], v[144:147], v[238:241], v[80:83]
	ds_read_b128 v[160:163], v168 offset:3088
	ds_read_b128 v[196:199], v169 offset:3088
	v_mfma_f32_16x16x32_f16 v[84:87], v[132:135], v[242:245], v[84:87]
	v_mfma_f32_16x16x32_f16 v[88:91], v[136:139], v[242:245], v[88:91]
	v_mfma_f32_16x16x32_f16 v[92:95], v[140:143], v[242:245], v[92:95]
	v_mfma_f32_16x16x32_f16 v[96:99], v[144:147], v[242:245], v[96:99]
	v_mfma_f32_16x16x32_f16 v[100:103], v[132:135], v[246:249], v[100:103]
	v_mfma_f32_16x16x32_f16 v[104:107], v[136:139], v[246:249], v[104:107]
	v_mfma_f32_16x16x32_f16 v[108:111], v[140:143], v[246:249], v[108:111]
	v_mfma_f32_16x16x32_f16 v[112:115], v[144:147], v[246:249], v[112:115]
	v_mfma_f32_16x16x32_f16 v[116:119], v[132:135], v[250:253], v[116:119]
	v_mfma_f32_16x16x32_f16 v[120:123], v[136:139], v[250:253], v[120:123]
	v_mfma_f32_16x16x32_f16 v[124:127], v[140:143], v[250:253], v[124:127]
	v_mfma_f32_16x16x32_f16 v[128:131], v[144:147], v[250:253], v[128:131]
	s_waitcnt lgkmcnt(0)
	s_mov_b32 s32, s37
	v_add_u32_e32 v169, s32, v164
	v_mfma_f32_16x16x32_f16 v[4:7], v[148:151], v[184:187], v[4:7]
	ds_read_b128 v[238:241], v169 offset:4112
	v_mfma_f32_16x16x32_f16 v[8:11], v[152:155], v[184:187], v[8:11]
	ds_read_b128 v[242:245], v169 offset:5136
	v_mfma_f32_16x16x32_f16 v[12:15], v[156:159], v[184:187], v[12:15]
	ds_read_b128 v[246:249], v169 offset:6160
	v_mfma_f32_16x16x32_f16 v[16:19], v[160:163], v[184:187], v[16:19]
	ds_read_b128 v[250:253], v169 offset:7184
	v_mfma_f32_16x16x32_f16 v[20:23], v[148:151], v[188:191], v[20:23]
	v_mfma_f32_16x16x32_f16 v[24:27], v[152:155], v[188:191], v[24:27]
	v_mfma_f32_16x16x32_f16 v[28:31], v[156:159], v[188:191], v[28:31]
	v_mfma_f32_16x16x32_f16 v[32:35], v[160:163], v[188:191], v[32:35]
	v_mfma_f32_16x16x32_f16 v[36:39], v[148:151], v[192:195], v[36:39]
	v_mfma_f32_16x16x32_f16 v[40:43], v[152:155], v[192:195], v[40:43]
	v_mfma_f32_16x16x32_f16 v[44:47], v[156:159], v[192:195], v[44:47]
	v_mfma_f32_16x16x32_f16 v[48:51], v[160:163], v[192:195], v[48:51]
	v_mfma_f32_16x16x32_f16 v[52:55], v[148:151], v[196:199], v[52:55]
	v_mfma_f32_16x16x32_f16 v[56:59], v[152:155], v[196:199], v[56:59]
	v_mfma_f32_16x16x32_f16 v[60:63], v[156:159], v[196:199], v[60:63]
	v_mfma_f32_16x16x32_f16 v[64:67], v[160:163], v[196:199], v[64:67]
	s_waitcnt lgkmcnt(0)
	s_barrier
	v_mfma_f32_16x16x32_f16 v[68:71], v[148:151], v[238:241], v[68:71]
	v_mfma_f32_16x16x32_f16 v[72:75], v[152:155], v[238:241], v[72:75]
	v_mfma_f32_16x16x32_f16 v[76:79], v[156:159], v[238:241], v[76:79]
	v_mfma_f32_16x16x32_f16 v[80:83], v[160:163], v[238:241], v[80:83]
	v_mfma_f32_16x16x32_f16 v[84:87], v[148:151], v[242:245], v[84:87]
	v_mfma_f32_16x16x32_f16 v[88:91], v[152:155], v[242:245], v[88:91]
	v_mfma_f32_16x16x32_f16 v[92:95], v[156:159], v[242:245], v[92:95]
	v_mfma_f32_16x16x32_f16 v[96:99], v[160:163], v[242:245], v[96:99]
	v_mfma_f32_16x16x32_f16 v[100:103], v[148:151], v[246:249], v[100:103]
	v_mfma_f32_16x16x32_f16 v[104:107], v[152:155], v[246:249], v[104:107]
	v_mfma_f32_16x16x32_f16 v[108:111], v[156:159], v[246:249], v[108:111]
	v_mfma_f32_16x16x32_f16 v[112:115], v[160:163], v[246:249], v[112:115]
	v_mfma_f32_16x16x32_f16 v[116:119], v[148:151], v[250:253], v[116:119]
	v_mfma_f32_16x16x32_f16 v[120:123], v[152:155], v[250:253], v[120:123]
	v_mfma_f32_16x16x32_f16 v[124:127], v[156:159], v[250:253], v[124:127]
	v_mfma_f32_16x16x32_f16 v[128:131], v[160:163], v[250:253], v[128:131]
	s_add_i32 s57, s56, s76
	s_cmp_ge_i32 s57, s58
	s_cbranch_scc1 .Lnopf_mlp1b
	s_lshr_b32 s77, s57, 4
	s_lshl_b32 s82, s77, 3
	s_or_b32 s82, s82, s83
	s_and_b64 s[80:81], s[74:75], exec
	s_cselect_b32 s32, s82, s77
	s_lshl_b32 s82, s77, 4
	s_sub_i32 s37, s57, s82
	s_lshl_b32 s37, s37, 8
	s_lshl_b32 s82, s32, 19
	s_add_u32 s68, s42, s82
	s_addc_u32 s69, s43, 0
	s_lshl_b32 s82, s37, 11
	s_add_u32 s80, s44, s82
	s_addc_u32 s81, s45, 0
	s_sub_u32 s82, s24, 16
	s_lshl_b32 s82, s82, 5
	s_add_u32 s68, s68, s82
	s_addc_u32 s69, s69, 0
	s_add_u32 s80, s80, s82
	s_addc_u32 s81, s81, 0
	v_bfe_u32 v172, v200, 6, 2
	v_bfe_u32 v173, v200, 4, 2
	v_lshlrev_b32_e32 v172, 6, v172
	v_lshl_or_b32 v172, v173, 2, v172
	v_add_u32_e32 v172, s37, v172
	v_lshlrev_b32_e32 v172, 2, v172
	global_load_dwordx4 v[132:135], v172, s[54:55]
	global_load_dwordx4 v[136:139], v172, s[54:55] offset:64
	global_load_dwordx4 v[140:143], v172, s[54:55] offset:128
	global_load_dwordx4 v[144:147], v172, s[54:55] offset:192
	s_mov_b32 s82, s24
	s_mov_b32 m0, s82
	s_nop 0
	global_load_lds_dwordx4 v170, s[68:69]
	s_add_u32 m0, s82, 0x400
	s_nop 0
	global_load_lds_dwordx4 v171, s[68:69]
	s_add_u32 m0, s82, 0x4000
	s_nop 0
	global_load_lds_dwordx4 v170, s[80:81]
	s_add_u32 m0, s82, 0x4400
	s_nop 0
	global_load_lds_dwordx4 v171, s[80:81]
	s_add_u32 s68, s68, 64
	s_addc_u32 s69, s69, 0
	s_add_u32 s80, s80, 64
	s_addc_u32 s81, s81, 0
	s_add_u32 s82, s24, 0x8000
	s_mov_b32 m0, s82
	s_nop 0
	global_load_lds_dwordx4 v170, s[68:69]
	s_add_u32 m0, s82, 0x400
	s_nop 0
	global_load_lds_dwordx4 v171, s[68:69]
	s_add_u32 m0, s82, 0x4000
	s_nop 0
	global_load_lds_dwordx4 v170, s[80:81]
	s_add_u32 m0, s82, 0x4400
	s_nop 0
	global_load_lds_dwordx4 v171, s[80:81]
	s_add_u32 s68, s68, 64
	s_addc_u32 s69, s69, 0
	s_add_u32 s80, s80, 64
	s_addc_u32 s81, s81, 0
	s_add_u32 s82, s24, 0x10000
	s_mov_b32 m0, s82
	s_nop 0
	global_load_lds_dwordx4 v170, s[68:69]
	s_add_u32 m0, s82, 0x400
	s_nop 0
	global_load_lds_dwordx4 v171, s[68:69]
	s_add_u32 m0, s82, 0x4000
	s_nop 0
	global_load_lds_dwordx4 v170, s[80:81]
	s_add_u32 m0, s82, 0x4400
	s_nop 0
	global_load_lds_dwordx4 v171, s[80:81]
	s_add_u32 s68, s68, 64
	s_addc_u32 s69, s69, 0
	s_add_u32 s80, s80, 64
	s_addc_u32 s81, s81, 0
	s_add_u32 s82, s24, 0x18000
	s_mov_b32 m0, s82
	s_nop 0
	global_load_lds_dwordx4 v170, s[68:69]
	s_add_u32 m0, s82, 0x400
	s_nop 0
	global_load_lds_dwordx4 v171, s[68:69]
	s_add_u32 m0, s82, 0x4000
	s_nop 0
	global_load_lds_dwordx4 v170, s[80:81]
	s_add_u32 m0, s82, 0x4400
	s_nop 0
	global_load_lds_dwordx4 v171, s[80:81]
	s_add_u32 s68, s68, 64
	s_addc_u32 s69, s69, 0
	s_add_u32 s80, s80, 64
	s_addc_u32 s81, s81, 0
.Lnopf_mlp1b:
	s_lshl_b64 s[80:81], s[28:29], 13
	s_add_u32 s80, s80, s34
	s_addc_u32 s81, s81, s35
	s_lshl_b32 s82, s65, 1
	s_add_u32 s80, s80, s82
	s_addc_u32 s81, s81, 0
	v_and_b32_e32 v172, 15, v200
	v_bfe_u32 v173, v200, 4, 2
	v_bfe_u32 v174, v200, 6, 2
	v_bfe_u32 v175, v200, 8, 1
	v_lshl_or_b32 v175, v175, 7, v172
	v_lshlrev_b32_e32 v175, 13, v175
	v_lshlrev_b32_e32 v174, 6, v174
	v_lshl_or_b32 v174, v173, 2, v174
	v_lshl_add_u32 v177, v174, 1, v175
	v_and_b32_e32 v172, 1, v173
	v_mul_u32_u24_e32 v172, 24, v172
	v_add_u32_e32 v177, v177, v172
	v_max_f32_e32 v4, 0, v4
	v_max_f32_e32 v5, 0, v5
	v_max_f32_e32 v6, 0, v6
	v_max_f32_e32 v7, 0, v7
	v_pk_mul_f32 v[4:5], v[4:5], v[4:5]
	v_pk_mul_f32 v[6:7], v[6:7], v[6:7]
	v_cvt_pk_f16_f32 v172, v4, v5
	v_cvt_pk_f16_f32 v173, v6, v7
	v_max_f32_e32 v8, 0, v8
	v_max_f32_e32 v9, 0, v9
	v_max_f32_e32 v10, 0, v10
	v_max_f32_e32 v11, 0, v11
	v_pk_mul_f32 v[8:9], v[8:9], v[8:9]
	v_pk_mul_f32 v[10:11], v[10:11], v[10:11]
	v_cvt_pk_f16_f32 v174, v8, v9
	v_cvt_pk_f16_f32 v175, v10, v11
	s_nop 1
	v_permlane16_swap_b32_e32 v172, v174
	v_permlane16_swap_b32_e32 v173, v175
	global_store_dwordx4 v177, v[172:175], s[80:81]
	v_max_f32_e32 v12, 0, v12
	v_max_f32_e32 v13, 0, v13
	v_max_f32_e32 v14, 0, v14
	v_max_f32_e32 v15, 0, v15
	v_pk_mul_f32 v[12:13], v[12:13], v[12:13]
	v_pk_mul_f32 v[14:15], v[14:15], v[14:15]
	v_cvt_pk_f16_f32 v228, v12, v13
	v_cvt_pk_f16_f32 v229, v14, v15
	v_max_f32_e32 v16, 0, v16
	v_max_f32_e32 v17, 0, v17
	v_max_f32_e32 v18, 0, v18
	v_max_f32_e32 v19, 0, v19
	v_pk_mul_f32 v[16:17], v[16:17], v[16:17]
	v_pk_mul_f32 v[18:19], v[18:19], v[18:19]
	v_cvt_pk_f16_f32 v230, v16, v17
	v_cvt_pk_f16_f32 v231, v18, v19
	s_nop 1
	v_permlane16_swap_b32_e32 v228, v230
	v_permlane16_swap_b32_e32 v229, v231
	global_store_dwordx4 v177, v[228:231], s[80:81] offset:64
	v_add_u32_e32 v177, 0x20000, v177
	v_max_f32_e32 v20, 0, v20
	v_max_f32_e32 v21, 0, v21
	v_max_f32_e32 v22, 0, v22
	v_max_f32_e32 v23, 0, v23
	v_pk_mul_f32 v[20:21], v[20:21], v[20:21]
	v_pk_mul_f32 v[22:23], v[22:23], v[22:23]
	v_cvt_pk_f16_f32 v172, v20, v21
	v_cvt_pk_f16_f32 v173, v22, v23
	v_max_f32_e32 v24, 0, v24
	v_max_f32_e32 v25, 0, v25
	v_max_f32_e32 v26, 0, v26
	v_max_f32_e32 v27, 0, v27
	v_pk_mul_f32 v[24:25], v[24:25], v[24:25]
	v_pk_mul_f32 v[26:27], v[26:27], v[26:27]
	v_cvt_pk_f16_f32 v174, v24, v25
	v_cvt_pk_f16_f32 v175, v26, v27
	s_nop 1
	v_permlane16_swap_b32_e32 v172, v174
	v_permlane16_swap_b32_e32 v173, v175
	global_store_dwordx4 v177, v[172:175], s[80:81]
	v_max_f32_e32 v28, 0, v28
	v_max_f32_e32 v29, 0, v29
	v_max_f32_e32 v30, 0, v30
	v_max_f32_e32 v31, 0, v31
	v_pk_mul_f32 v[28:29], v[28:29], v[28:29]
	v_pk_mul_f32 v[30:31], v[30:31], v[30:31]
	v_cvt_pk_f16_f32 v228, v28, v29
	v_cvt_pk_f16_f32 v229, v30, v31
	v_max_f32_e32 v32, 0, v32
	v_max_f32_e32 v33, 0, v33
	v_max_f32_e32 v34, 0, v34
	v_max_f32_e32 v35, 0, v35
	v_pk_mul_f32 v[32:33], v[32:33], v[32:33]
	v_pk_mul_f32 v[34:35], v[34:35], v[34:35]
	v_cvt_pk_f16_f32 v230, v32, v33
	v_cvt_pk_f16_f32 v231, v34, v35
	s_nop 1
	v_permlane16_swap_b32_e32 v228, v230
	v_permlane16_swap_b32_e32 v229, v231
	global_store_dwordx4 v177, v[228:231], s[80:81] offset:64
	v_add_u32_e32 v177, 0x20000, v177
	v_max_f32_e32 v36, 0, v36
	v_max_f32_e32 v37, 0, v37
	v_max_f32_e32 v38, 0, v38
	v_max_f32_e32 v39, 0, v39
	v_pk_mul_f32 v[36:37], v[36:37], v[36:37]
	v_pk_mul_f32 v[38:39], v[38:39], v[38:39]
	v_cvt_pk_f16_f32 v172, v36, v37
	v_cvt_pk_f16_f32 v173, v38, v39
	v_max_f32_e32 v40, 0, v40
	v_max_f32_e32 v41, 0, v41
	v_max_f32_e32 v42, 0, v42
	v_max_f32_e32 v43, 0, v43
	v_pk_mul_f32 v[40:41], v[40:41], v[40:41]
	v_pk_mul_f32 v[42:43], v[42:43], v[42:43]
	v_cvt_pk_f16_f32 v174, v40, v41
	v_cvt_pk_f16_f32 v175, v42, v43
	s_nop 1
	v_permlane16_swap_b32_e32 v172, v174
	v_permlane16_swap_b32_e32 v173, v175
	global_store_dwordx4 v177, v[172:175], s[80:81]
	v_max_f32_e32 v44, 0, v44
	v_max_f32_e32 v45, 0, v45
	v_max_f32_e32 v46, 0, v46
	v_max_f32_e32 v47, 0, v47
	v_pk_mul_f32 v[44:45], v[44:45], v[44:45]
	v_pk_mul_f32 v[46:47], v[46:47], v[46:47]
	v_cvt_pk_f16_f32 v228, v44, v45
	v_cvt_pk_f16_f32 v229, v46, v47
	v_max_f32_e32 v48, 0, v48
	v_max_f32_e32 v49, 0, v49
	v_max_f32_e32 v50, 0, v50
	v_max_f32_e32 v51, 0, v51
	v_pk_mul_f32 v[48:49], v[48:49], v[48:49]
	v_pk_mul_f32 v[50:51], v[50:51], v[50:51]
	v_cvt_pk_f16_f32 v230, v48, v49
	v_cvt_pk_f16_f32 v231, v50, v51
	s_nop 1
	v_permlane16_swap_b32_e32 v228, v230
	v_permlane16_swap_b32_e32 v229, v231
	global_store_dwordx4 v177, v[228:231], s[80:81] offset:64
	v_add_u32_e32 v177, 0x20000, v177
	v_max_f32_e32 v52, 0, v52
	v_max_f32_e32 v53, 0, v53
	v_max_f32_e32 v54, 0, v54
	v_max_f32_e32 v55, 0, v55
	v_pk_mul_f32 v[52:53], v[52:53], v[52:53]
	v_pk_mul_f32 v[54:55], v[54:55], v[54:55]
	v_cvt_pk_f16_f32 v172, v52, v53
	v_cvt_pk_f16_f32 v173, v54, v55
	v_max_f32_e32 v56, 0, v56
	v_max_f32_e32 v57, 0, v57
	v_max_f32_e32 v58, 0, v58
	v_max_f32_e32 v59, 0, v59
	v_pk_mul_f32 v[56:57], v[56:57], v[56:57]
	v_pk_mul_f32 v[58:59], v[58:59], v[58:59]
	v_cvt_pk_f16_f32 v174, v56, v57
	v_cvt_pk_f16_f32 v175, v58, v59
	s_nop 1
	v_permlane16_swap_b32_e32 v172, v174
	v_permlane16_swap_b32_e32 v173, v175
	global_store_dwordx4 v177, v[172:175], s[80:81]
	v_max_f32_e32 v60, 0, v60
	v_max_f32_e32 v61, 0, v61
	v_max_f32_e32 v62, 0, v62
	v_max_f32_e32 v63, 0, v63
	v_pk_mul_f32 v[60:61], v[60:61], v[60:61]
	v_pk_mul_f32 v[62:63], v[62:63], v[62:63]
	v_cvt_pk_f16_f32 v228, v60, v61
	v_cvt_pk_f16_f32 v229, v62, v63
	v_max_f32_e32 v64, 0, v64
	v_max_f32_e32 v65, 0, v65
	v_max_f32_e32 v66, 0, v66
	v_max_f32_e32 v67, 0, v67
	v_pk_mul_f32 v[64:65], v[64:65], v[64:65]
	v_pk_mul_f32 v[66:67], v[66:67], v[66:67]
	v_cvt_pk_f16_f32 v230, v64, v65
	v_cvt_pk_f16_f32 v231, v66, v67
	s_nop 1
	v_permlane16_swap_b32_e32 v228, v230
	v_permlane16_swap_b32_e32 v229, v231
	global_store_dwordx4 v177, v[228:231], s[80:81] offset:64
	v_add_u32_e32 v177, 0x20000, v177
	v_max_f32_e32 v68, 0, v68
	v_max_f32_e32 v69, 0, v69
	v_max_f32_e32 v70, 0, v70
	v_max_f32_e32 v71, 0, v71
	v_pk_mul_f32 v[68:69], v[68:69], v[68:69]
	v_pk_mul_f32 v[70:71], v[70:71], v[70:71]
	v_cvt_pk_f16_f32 v172, v68, v69
	v_cvt_pk_f16_f32 v173, v70, v71
	v_max_f32_e32 v72, 0, v72
	v_max_f32_e32 v73, 0, v73
	v_max_f32_e32 v74, 0, v74
	v_max_f32_e32 v75, 0, v75
	v_pk_mul_f32 v[72:73], v[72:73], v[72:73]
	v_pk_mul_f32 v[74:75], v[74:75], v[74:75]
	v_cvt_pk_f16_f32 v174, v72, v73
	v_cvt_pk_f16_f32 v175, v74, v75
	s_nop 1
	v_permlane16_swap_b32_e32 v172, v174
	v_permlane16_swap_b32_e32 v173, v175
	global_store_dwordx4 v177, v[172:175], s[80:81]
	v_max_f32_e32 v76, 0, v76
	v_max_f32_e32 v77, 0, v77
	v_max_f32_e32 v78, 0, v78
	v_max_f32_e32 v79, 0, v79
	v_pk_mul_f32 v[76:77], v[76:77], v[76:77]
	v_pk_mul_f32 v[78:79], v[78:79], v[78:79]
	v_cvt_pk_f16_f32 v228, v76, v77
	v_cvt_pk_f16_f32 v229, v78, v79
	v_max_f32_e32 v80, 0, v80
	v_max_f32_e32 v81, 0, v81
	v_max_f32_e32 v82, 0, v82
	v_max_f32_e32 v83, 0, v83
	v_pk_mul_f32 v[80:81], v[80:81], v[80:81]
	v_pk_mul_f32 v[82:83], v[82:83], v[82:83]
	v_cvt_pk_f16_f32 v230, v80, v81
	v_cvt_pk_f16_f32 v231, v82, v83
	s_nop 1
	v_permlane16_swap_b32_e32 v228, v230
	v_permlane16_swap_b32_e32 v229, v231
	global_store_dwordx4 v177, v[228:231], s[80:81] offset:64
	v_add_u32_e32 v177, 0x20000, v177
	v_max_f32_e32 v84, 0, v84
	v_max_f32_e32 v85, 0, v85
	v_max_f32_e32 v86, 0, v86
	v_max_f32_e32 v87, 0, v87
	v_pk_mul_f32 v[84:85], v[84:85], v[84:85]
	v_pk_mul_f32 v[86:87], v[86:87], v[86:87]
	v_cvt_pk_f16_f32 v172, v84, v85
	v_cvt_pk_f16_f32 v173, v86, v87
	v_max_f32_e32 v88, 0, v88
	v_max_f32_e32 v89, 0, v89
	v_max_f32_e32 v90, 0, v90
	v_max_f32_e32 v91, 0, v91
	v_pk_mul_f32 v[88:89], v[88:89], v[88:89]
	v_pk_mul_f32 v[90:91], v[90:91], v[90:91]
	v_cvt_pk_f16_f32 v174, v88, v89
	v_cvt_pk_f16_f32 v175, v90, v91
	s_nop 1
	v_permlane16_swap_b32_e32 v172, v174
	v_permlane16_swap_b32_e32 v173, v175
	global_store_dwordx4 v177, v[172:175], s[80:81]
	v_max_f32_e32 v92, 0, v92
	v_max_f32_e32 v93, 0, v93
	v_max_f32_e32 v94, 0, v94
	v_max_f32_e32 v95, 0, v95
	v_pk_mul_f32 v[92:93], v[92:93], v[92:93]
	v_pk_mul_f32 v[94:95], v[94:95], v[94:95]
	v_cvt_pk_f16_f32 v228, v92, v93
	v_cvt_pk_f16_f32 v229, v94, v95
	v_max_f32_e32 v96, 0, v96
	v_max_f32_e32 v97, 0, v97
	v_max_f32_e32 v98, 0, v98
	v_max_f32_e32 v99, 0, v99
	v_pk_mul_f32 v[96:97], v[96:97], v[96:97]
	v_pk_mul_f32 v[98:99], v[98:99], v[98:99]
	v_cvt_pk_f16_f32 v230, v96, v97
	v_cvt_pk_f16_f32 v231, v98, v99
	s_nop 1
	v_permlane16_swap_b32_e32 v228, v230
	v_permlane16_swap_b32_e32 v229, v231
	global_store_dwordx4 v177, v[228:231], s[80:81] offset:64
	v_add_u32_e32 v177, 0x20000, v177
	v_max_f32_e32 v100, 0, v100
	v_max_f32_e32 v101, 0, v101
	v_max_f32_e32 v102, 0, v102
	v_max_f32_e32 v103, 0, v103
	v_pk_mul_f32 v[100:101], v[100:101], v[100:101]
	v_pk_mul_f32 v[102:103], v[102:103], v[102:103]
	v_cvt_pk_f16_f32 v172, v100, v101
	v_cvt_pk_f16_f32 v173, v102, v103
	v_max_f32_e32 v104, 0, v104
	v_max_f32_e32 v105, 0, v105
	v_max_f32_e32 v106, 0, v106
	v_max_f32_e32 v107, 0, v107
	v_pk_mul_f32 v[104:105], v[104:105], v[104:105]
	v_pk_mul_f32 v[106:107], v[106:107], v[106:107]
	v_cvt_pk_f16_f32 v174, v104, v105
	v_cvt_pk_f16_f32 v175, v106, v107
	s_nop 1
	v_permlane16_swap_b32_e32 v172, v174
	v_permlane16_swap_b32_e32 v173, v175
	global_store_dwordx4 v177, v[172:175], s[80:81]
	v_max_f32_e32 v108, 0, v108
	v_max_f32_e32 v109, 0, v109
	v_max_f32_e32 v110, 0, v110
	v_max_f32_e32 v111, 0, v111
	v_pk_mul_f32 v[108:109], v[108:109], v[108:109]
	v_pk_mul_f32 v[110:111], v[110:111], v[110:111]
	v_cvt_pk_f16_f32 v228, v108, v109
	v_cvt_pk_f16_f32 v229, v110, v111
	v_max_f32_e32 v112, 0, v112
	v_max_f32_e32 v113, 0, v113
	v_max_f32_e32 v114, 0, v114
	v_max_f32_e32 v115, 0, v115
	v_pk_mul_f32 v[112:113], v[112:113], v[112:113]
	v_pk_mul_f32 v[114:115], v[114:115], v[114:115]
	v_cvt_pk_f16_f32 v230, v112, v113
	v_cvt_pk_f16_f32 v231, v114, v115
	s_nop 1
	v_permlane16_swap_b32_e32 v228, v230
	v_permlane16_swap_b32_e32 v229, v231
	global_store_dwordx4 v177, v[228:231], s[80:81] offset:64
	v_add_u32_e32 v177, 0x20000, v177
	v_max_f32_e32 v116, 0, v116
	v_max_f32_e32 v117, 0, v117
	v_max_f32_e32 v118, 0, v118
	v_max_f32_e32 v119, 0, v119
	v_pk_mul_f32 v[116:117], v[116:117], v[116:117]
	v_pk_mul_f32 v[118:119], v[118:119], v[118:119]
	v_cvt_pk_f16_f32 v172, v116, v117
	v_cvt_pk_f16_f32 v173, v118, v119
	v_max_f32_e32 v120, 0, v120
	v_max_f32_e32 v121, 0, v121
	v_max_f32_e32 v122, 0, v122
	v_max_f32_e32 v123, 0, v123
	v_pk_mul_f32 v[120:121], v[120:121], v[120:121]
	v_pk_mul_f32 v[122:123], v[122:123], v[122:123]
	v_cvt_pk_f16_f32 v174, v120, v121
	v_cvt_pk_f16_f32 v175, v122, v123
	s_nop 1
	v_permlane16_swap_b32_e32 v172, v174
	v_permlane16_swap_b32_e32 v173, v175
	global_store_dwordx4 v177, v[172:175], s[80:81]
	v_max_f32_e32 v124, 0, v124
	v_max_f32_e32 v125, 0, v125
	v_max_f32_e32 v126, 0, v126
	v_max_f32_e32 v127, 0, v127
	v_pk_mul_f32 v[124:125], v[124:125], v[124:125]
	v_pk_mul_f32 v[126:127], v[126:127], v[126:127]
	v_cvt_pk_f16_f32 v228, v124, v125
	v_cvt_pk_f16_f32 v229, v126, v127
	v_max_f32_e32 v128, 0, v128
	v_max_f32_e32 v129, 0, v129
	v_max_f32_e32 v130, 0, v130
	v_max_f32_e32 v131, 0, v131
	v_pk_mul_f32 v[128:129], v[128:129], v[128:129]
	v_pk_mul_f32 v[130:131], v[130:131], v[130:131]
	v_cvt_pk_f16_f32 v230, v128, v129
	v_cvt_pk_f16_f32 v231, v130, v131
	s_nop 1
	v_permlane16_swap_b32_e32 v228, v230
	v_permlane16_swap_b32_e32 v229, v231
	global_store_dwordx4 v177, v[228:231], s[80:81] offset:64
	s_nop 1
	s_cmp_ge_i32 s57, s58
	s_cbranch_scc1 .LBB0_127
	s_mov_b32 s56, s57
	s_ashr_i32 s24, s56, 31
	s_lshr_b32 s24, s24, 28
	s_add_i32 s24, s56, s24
	s_ashr_i32 s25, s24, 4
	s_lshl_b32 s24, s25, 3
	s_or_b32 s24, s24, s83
	s_and_b64 s[28:29], s[74:75], exec
	s_cselect_b32 s24, s24, s25
	s_lshl_b32 s36, s24, 8
	s_cmp_gt_i32 s24, 39
	s_mov_b64 s[30:31], -1
	s_cbranch_scc0 .Lpfh_mlp1b_113
	s_add_i32 s90, s36, 0xffffd800
	s_mov_b64 s[30:31], 0
	s_mov_b64 s[28:29], s[90:91]

.Lpfh_mlp1b_115:
	s_lshl_b32 s65, s25, 4
	s_sub_i32 s65, s56, s65
	s_lshl_b32 s65, s65, 8
	s_lshl_b32 vcc_hi, s36, 11
	s_add_u32 s30, s42, vcc_hi
	s_addc_u32 s31, s43, 0
	s_lshl_b32 vcc_hi, s65, 11
	s_add_u32 s52, s44, vcc_hi
	s_addc_u32 s53, s45, 0
	s_waitcnt lgkmcnt(0)
	v_readfirstlane_b32 vcc_hi, v200
	s_lshr_b32 vcc_hi, vcc_hi, 6
	s_lshl_b32 s24, vcc_hi, 11
	s_add_u32 s24, s24, 16
	s_lshl_b32 vcc_hi, vcc_hi, 16
	s_add_u32 s30, s30, vcc_hi
	s_addc_u32 s31, s31, 0
	s_add_u32 s52, s52, vcc_hi
	s_addc_u32 s53, s53, 0
	s_add_u32 s30, s30, 256
	s_addc_u32 s31, s31, 0
	s_add_u32 s52, s52, 256
	s_addc_u32 s53, s53, 0
	s_waitcnt vmcnt(16)
	v_mov_b32_e32 v4, v132
	v_mov_b32_e32 v5, v133
	v_mov_b32_e32 v6, v134
	v_mov_b32_e32 v7, v135
	v_mov_b32_e32 v8, v136
	v_mov_b32_e32 v9, v137
	v_mov_b32_e32 v10, v138
	v_mov_b32_e32 v11, v139
	v_mov_b32_e32 v12, v140
	v_mov_b32_e32 v13, v141
	v_mov_b32_e32 v14, v142
	v_mov_b32_e32 v15, v143
	v_mov_b32_e32 v16, v144
	v_mov_b32_e32 v17, v145
	v_mov_b32_e32 v18, v146
	v_mov_b32_e32 v19, v147
	v_mov_b32_e32 v20, v132
	v_mov_b32_e32 v21, v133
	v_mov_b32_e32 v22, v134
	v_mov_b32_e32 v23, v135
	v_mov_b32_e32 v24, v136
	v_mov_b32_e32 v25, v137
	v_mov_b32_e32 v26, v138
	v_mov_b32_e32 v27, v139
	v_mov_b32_e32 v28, v140
	v_mov_b32_e32 v29, v141
	v_mov_b32_e32 v30, v142
	v_mov_b32_e32 v31, v143
	v_mov_b32_e32 v32, v144
	v_mov_b32_e32 v33, v145
	v_mov_b32_e32 v34, v146
	v_mov_b32_e32 v35, v147
	v_mov_b32_e32 v36, v132
	v_mov_b32_e32 v37, v133
	v_mov_b32_e32 v38, v134
	v_mov_b32_e32 v39, v135
	v_mov_b32_e32 v40, v136
	v_mov_b32_e32 v41, v137
	v_mov_b32_e32 v42, v138
	v_mov_b32_e32 v43, v139
	v_mov_b32_e32 v44, v140
	v_mov_b32_e32 v45, v141
	v_mov_b32_e32 v46, v142
	v_mov_b32_e32 v47, v143
	v_mov_b32_e32 v48, v144
	v_mov_b32_e32 v49, v145
	v_mov_b32_e32 v50, v146
	v_mov_b32_e32 v51, v147
	v_mov_b32_e32 v52, v132
	v_mov_b32_e32 v53, v133
	v_mov_b32_e32 v54, v134
	v_mov_b32_e32 v55, v135
	v_mov_b32_e32 v56, v136
	v_mov_b32_e32 v57, v137
	v_mov_b32_e32 v58, v138
	v_mov_b32_e32 v59, v139
	v_mov_b32_e32 v60, v140
	v_mov_b32_e32 v61, v141
	v_mov_b32_e32 v62, v142
	v_mov_b32_e32 v63, v143
	v_mov_b32_e32 v64, v144
	v_mov_b32_e32 v65, v145
	v_mov_b32_e32 v66, v146
	v_mov_b32_e32 v67, v147
	v_mov_b32_e32 v68, v132
	v_mov_b32_e32 v69, v133
	v_mov_b32_e32 v70, v134
	v_mov_b32_e32 v71, v135
	v_mov_b32_e32 v72, v136
	v_mov_b32_e32 v73, v137
	v_mov_b32_e32 v74, v138
	v_mov_b32_e32 v75, v139
	v_mov_b32_e32 v76, v140
	v_mov_b32_e32 v77, v141
	v_mov_b32_e32 v78, v142
	v_mov_b32_e32 v79, v143
	v_mov_b32_e32 v80, v144
	v_mov_b32_e32 v81, v145
	v_mov_b32_e32 v82, v146
	v_mov_b32_e32 v83, v147
	v_mov_b32_e32 v84, v132
	v_mov_b32_e32 v85, v133
	v_mov_b32_e32 v86, v134
	v_mov_b32_e32 v87, v135
	v_mov_b32_e32 v88, v136
	v_mov_b32_e32 v89, v137
	v_mov_b32_e32 v90, v138
	v_mov_b32_e32 v91, v139
	v_mov_b32_e32 v92, v140
	v_mov_b32_e32 v93, v141
	v_mov_b32_e32 v94, v142
	v_mov_b32_e32 v95, v143
	v_mov_b32_e32 v96, v144
	v_mov_b32_e32 v97, v145
	v_mov_b32_e32 v98, v146
	v_mov_b32_e32 v99, v147
	v_mov_b32_e32 v100, v132
	v_mov_b32_e32 v101, v133
	v_mov_b32_e32 v102, v134
	v_mov_b32_e32 v103, v135
	v_mov_b32_e32 v104, v136
	v_mov_b32_e32 v105, v137
	v_mov_b32_e32 v106, v138
	v_mov_b32_e32 v107, v139
	v_mov_b32_e32 v108, v140
	v_mov_b32_e32 v109, v141
	v_mov_b32_e32 v110, v142
	v_mov_b32_e32 v111, v143
	v_mov_b32_e32 v112, v144
	v_mov_b32_e32 v113, v145
	v_mov_b32_e32 v114, v146
	v_mov_b32_e32 v115, v147
	v_mov_b32_e32 v116, v132
	v_mov_b32_e32 v117, v133
	v_mov_b32_e32 v118, v134
	v_mov_b32_e32 v119, v135
	v_mov_b32_e32 v120, v136
	v_mov_b32_e32 v121, v137
	v_mov_b32_e32 v122, v138
	v_mov_b32_e32 v123, v139
	v_mov_b32_e32 v124, v140
	v_mov_b32_e32 v125, v141
	v_mov_b32_e32 v126, v142
	v_mov_b32_e32 v127, v143
	v_mov_b32_e32 v128, v144
	v_mov_b32_e32 v129, v145
	v_mov_b32_e32 v130, v146
	v_mov_b32_e32 v131, v147
	s_barrier
	s_branch .Lmain_mlp1b

.Lmain_mlp1a:
	s_mov_b32 s37, 0
	s_mov_b32 s55, 0
	s_nop 1
	v_add_u32_e32 v168, s37, v165
	v_add_u32_e32 v169, s37, v164
	ds_read_b128 v[132:135], v168 offset:16
	ds_read_b128 v[136:139], v168 offset:1040
	ds_read_b128 v[140:143], v168 offset:2064
	ds_read_b128 v[144:147], v168 offset:3088
	ds_read_b128 v[184:187], v169 offset:16
	ds_read_b128 v[188:191], v169 offset:1040
	ds_read_b128 v[192:195], v169 offset:2064
	ds_read_b128 v[196:199], v169 offset:3088
	s_waitcnt lgkmcnt(0)
.Lt_mlp1a:
	v_add_u32_e32 v169, s37, v164
	v_mfma_f32_16x16x32_f16 v[4:7], v[132:135], v[184:187], v[4:7]
	ds_read_b128 v[238:241], v169 offset:4112
	v_mfma_f32_16x16x32_f16 v[8:11], v[136:139], v[184:187], v[8:11]
	ds_read_b128 v[242:245], v169 offset:5136
	v_mfma_f32_16x16x32_f16 v[12:15], v[140:143], v[184:187], v[12:15]
	ds_read_b128 v[246:249], v169 offset:6160
	v_mfma_f32_16x16x32_f16 v[16:19], v[144:147], v[184:187], v[16:19]
	ds_read_b128 v[250:253], v169 offset:7184
	v_mfma_f32_16x16x32_f16 v[20:23], v[132:135], v[188:191], v[20:23]
	v_mfma_f32_16x16x32_f16 v[24:27], v[136:139], v[188:191], v[24:27]
	v_mfma_f32_16x16x32_f16 v[28:31], v[140:143], v[188:191], v[28:31]
	v_mfma_f32_16x16x32_f16 v[32:35], v[144:147], v[188:191], v[32:35]
	v_mfma_f32_16x16x32_f16 v[36:39], v[132:135], v[192:195], v[36:39]
	v_mfma_f32_16x16x32_f16 v[40:43], v[136:139], v[192:195], v[40:43]
	v_mfma_f32_16x16x32_f16 v[44:47], v[140:143], v[192:195], v[44:47]
	v_mfma_f32_16x16x32_f16 v[48:51], v[144:147], v[192:195], v[48:51]
	v_mfma_f32_16x16x32_f16 v[52:55], v[132:135], v[196:199], v[52:55]
	v_mfma_f32_16x16x32_f16 v[56:59], v[136:139], v[196:199], v[56:59]
	v_mfma_f32_16x16x32_f16 v[60:63], v[140:143], v[196:199], v[60:63]
	v_mfma_f32_16x16x32_f16 v[64:67], v[144:147], v[196:199], v[64:67]
	s_waitcnt vmcnt(8) lgkmcnt(0)
	s_barrier
	s_add_i32 s53, s37, 0x8000
	s_cmp_lg_u32 s37, 0x18000
	s_cselect_b32 s53, s53, 0
	v_add_u32_e32 v168, s53, v165
	v_add_u32_e32 v169, s53, v164
	s_add_u32 vcc_lo, s32, s37
	v_mfma_f32_16x16x32_f16 v[68:71], v[132:135], v[238:241], v[68:71]
	ds_read_b128 v[148:151], v168 offset:16
	ds_read_b128 v[184:187], v169 offset:16
	v_mfma_f32_16x16x32_f16 v[72:75], v[136:139], v[238:241], v[72:75]
	ds_read_b128 v[152:155], v168 offset:1040
	ds_read_b128 v[188:191], v169 offset:1040
	v_mfma_f32_16x16x32_f16 v[76:79], v[140:143], v[238:241], v[76:79]
	ds_read_b128 v[156:159], v168 offset:2064
	ds_read_b128 v[192:195], v169 offset:2064
	v_mfma_f32_16x16x32_f16 v[80:83], v[144:147], v[238:241], v[80:83]
	ds_read_b128 v[160:163], v168 offset:3088
	ds_read_b128 v[196:199], v169 offset:3088
	v_mfma_f32_16x16x32_f16 v[84:87], v[132:135], v[242:245], v[84:87]
	v_mfma_f32_16x16x32_f16 v[88:91], v[136:139], v[242:245], v[88:91]
	v_mfma_f32_16x16x32_f16 v[92:95], v[140:143], v[242:245], v[92:95]
	v_mfma_f32_16x16x32_f16 v[96:99], v[144:147], v[242:245], v[96:99]
	v_mfma_f32_16x16x32_f16 v[100:103], v[132:135], v[246:249], v[100:103]
	s_mov_b32 m0, vcc_lo
	s_nop 0
	global_load_lds_dwordx4 v170, s[30:31]
	v_mfma_f32_16x16x32_f16 v[104:107], v[136:139], v[246:249], v[104:107]
	s_add_u32 m0, vcc_lo, 0x400
	s_nop 0
	global_load_lds_dwordx4 v171, s[30:31]
	v_mfma_f32_16x16x32_f16 v[108:111], v[140:143], v[246:249], v[108:111]
	s_add_u32 m0, vcc_lo, 0x4000
	s_nop 0
	global_load_lds_dwordx4 v170, s[56:57]
	v_mfma_f32_16x16x32_f16 v[112:115], v[144:147], v[246:249], v[112:115]
	s_add_u32 m0, vcc_lo, 0x4400
	s_nop 0
	global_load_lds_dwordx4 v171, s[56:57]
	v_mfma_f32_16x16x32_f16 v[116:119], v[132:135], v[250:253], v[116:119]
	v_mfma_f32_16x16x32_f16 v[120:123], v[136:139], v[250:253], v[120:123]
	v_mfma_f32_16x16x32_f16 v[124:127], v[140:143], v[250:253], v[124:127]
	v_mfma_f32_16x16x32_f16 v[128:131], v[144:147], v[250:253], v[128:131]
	s_waitcnt lgkmcnt(0)
	s_mov_b32 s37, s53
	s_add_u32 s30, s30, 64
	s_addc_u32 s31, s31, 0
	s_add_u32 s56, s56, 64
	s_addc_u32 s57, s57, 0
	v_add_u32_e32 v169, s37, v164
	v_mfma_f32_16x16x32_f16 v[4:7], v[148:151], v[184:187], v[4:7]
	ds_read_b128 v[238:241], v169 offset:4112
	v_mfma_f32_16x16x32_f16 v[8:11], v[152:155], v[184:187], v[8:11]
	ds_read_b128 v[242:245], v169 offset:5136
	v_mfma_f32_16x16x32_f16 v[12:15], v[156:159], v[184:187], v[12:15]
	ds_read_b128 v[246:249], v169 offset:6160
	v_mfma_f32_16x16x32_f16 v[16:19], v[160:163], v[184:187], v[16:19]
	ds_read_b128 v[250:253], v169 offset:7184
	v_mfma_f32_16x16x32_f16 v[20:23], v[148:151], v[188:191], v[20:23]
	v_mfma_f32_16x16x32_f16 v[24:27], v[152:155], v[188:191], v[24:27]
	v_mfma_f32_16x16x32_f16 v[28:31], v[156:159], v[188:191], v[28:31]
	v_mfma_f32_16x16x32_f16 v[32:35], v[160:163], v[188:191], v[32:35]
	v_mfma_f32_16x16x32_f16 v[36:39], v[148:151], v[192:195], v[36:39]
	v_mfma_f32_16x16x32_f16 v[40:43], v[152:155], v[192:195], v[40:43]
	v_mfma_f32_16x16x32_f16 v[44:47], v[156:159], v[192:195], v[44:47]
	v_mfma_f32_16x16x32_f16 v[48:51], v[160:163], v[192:195], v[48:51]
	v_mfma_f32_16x16x32_f16 v[52:55], v[148:151], v[196:199], v[52:55]
	v_mfma_f32_16x16x32_f16 v[56:59], v[152:155], v[196:199], v[56:59]
	v_mfma_f32_16x16x32_f16 v[60:63], v[156:159], v[196:199], v[60:63]
	v_mfma_f32_16x16x32_f16 v[64:67], v[160:163], v[196:199], v[64:67]
	s_waitcnt vmcnt(8) lgkmcnt(0)
	s_barrier
	s_add_i32 s53, s37, 0x8000
	s_cmp_lg_u32 s37, 0x18000
	s_cselect_b32 s53, s53, 0
	v_add_u32_e32 v168, s53, v165
	v_add_u32_e32 v169, s53, v164
	s_add_u32 vcc_lo, s32, s37
	v_mfma_f32_16x16x32_f16 v[68:71], v[148:151], v[238:241], v[68:71]
	ds_read_b128 v[132:135], v168 offset:16
	ds_read_b128 v[184:187], v169 offset:16
	v_mfma_f32_16x16x32_f16 v[72:75], v[152:155], v[238:241], v[72:75]
	ds_read_b128 v[136:139], v168 offset:1040
	ds_read_b128 v[188:191], v169 offset:1040
	v_mfma_f32_16x16x32_f16 v[76:79], v[156:159], v[238:241], v[76:79]
	ds_read_b128 v[140:143], v168 offset:2064
	ds_read_b128 v[192:195], v169 offset:2064
	v_mfma_f32_16x16x32_f16 v[80:83], v[160:163], v[238:241], v[80:83]
	ds_read_b128 v[144:147], v168 offset:3088
	ds_read_b128 v[196:199], v169 offset:3088
	v_mfma_f32_16x16x32_f16 v[84:87], v[148:151], v[242:245], v[84:87]
	v_mfma_f32_16x16x32_f16 v[88:91], v[152:155], v[242:245], v[88:91]
	v_mfma_f32_16x16x32_f16 v[92:95], v[156:159], v[242:245], v[92:95]
	v_mfma_f32_16x16x32_f16 v[96:99], v[160:163], v[242:245], v[96:99]
	v_mfma_f32_16x16x32_f16 v[100:103], v[148:151], v[246:249], v[100:103]
	s_mov_b32 m0, vcc_lo
	s_nop 0
	global_load_lds_dwordx4 v170, s[30:31]
	v_mfma_f32_16x16x32_f16 v[104:107], v[152:155], v[246:249], v[104:107]
	s_add_u32 m0, vcc_lo, 0x400
	s_nop 0
	global_load_lds_dwordx4 v171, s[30:31]
	v_mfma_f32_16x16x32_f16 v[108:111], v[156:159], v[246:249], v[108:111]
	s_add_u32 m0, vcc_lo, 0x4000
	s_nop 0
	global_load_lds_dwordx4 v170, s[56:57]
	v_mfma_f32_16x16x32_f16 v[112:115], v[160:163], v[246:249], v[112:115]
	s_add_u32 m0, vcc_lo, 0x4400
	s_nop 0
	global_load_lds_dwordx4 v171, s[56:57]
	v_mfma_f32_16x16x32_f16 v[116:119], v[148:151], v[250:253], v[116:119]
	v_mfma_f32_16x16x32_f16 v[120:123], v[152:155], v[250:253], v[120:123]
	v_mfma_f32_16x16x32_f16 v[124:127], v[156:159], v[250:253], v[124:127]
	v_mfma_f32_16x16x32_f16 v[128:131], v[160:163], v[250:253], v[128:131]
	s_waitcnt lgkmcnt(0)
	s_mov_b32 s37, s53
	s_add_u32 s30, s30, 64
	s_addc_u32 s31, s31, 0
	s_add_u32 s56, s56, 64
	s_addc_u32 s57, s57, 0
	s_add_i32 s55, s55, 2
	s_cmp_lt_u32 s55, 28
	s_cbranch_scc1 .Lt_mlp1a
	v_add_u32_e32 v169, s37, v164
	v_mfma_f32_16x16x32_f16 v[4:7], v[132:135], v[184:187], v[4:7]
	ds_read_b128 v[238:241], v169 offset:4112
	v_mfma_f32_16x16x32_f16 v[8:11], v[136:139], v[184:187], v[8:11]
	ds_read_b128 v[242:245], v169 offset:5136
	v_mfma_f32_16x16x32_f16 v[12:15], v[140:143], v[184:187], v[12:15]
	ds_read_b128 v[246:249], v169 offset:6160
	v_mfma_f32_16x16x32_f16 v[16:19], v[144:147], v[184:187], v[16:19]
	ds_read_b128 v[250:253], v169 offset:7184
	v_mfma_f32_16x16x32_f16 v[20:23], v[132:135], v[188:191], v[20:23]
	v_mfma_f32_16x16x32_f16 v[24:27], v[136:139], v[188:191], v[24:27]
	v_mfma_f32_16x16x32_f16 v[28:31], v[140:143], v[188:191], v[28:31]
	v_mfma_f32_16x16x32_f16 v[32:35], v[144:147], v[188:191], v[32:35]
	v_mfma_f32_16x16x32_f16 v[36:39], v[132:135], v[192:195], v[36:39]
	v_mfma_f32_16x16x32_f16 v[40:43], v[136:139], v[192:195], v[40:43]
	v_mfma_f32_16x16x32_f16 v[44:47], v[140:143], v[192:195], v[44:47]
	v_mfma_f32_16x16x32_f16 v[48:51], v[144:147], v[192:195], v[48:51]
	v_mfma_f32_16x16x32_f16 v[52:55], v[132:135], v[196:199], v[52:55]
	v_mfma_f32_16x16x32_f16 v[56:59], v[136:139], v[196:199], v[56:59]
	v_mfma_f32_16x16x32_f16 v[60:63], v[140:143], v[196:199], v[60:63]
	v_mfma_f32_16x16x32_f16 v[64:67], v[144:147], v[196:199], v[64:67]
	s_waitcnt vmcnt(8) lgkmcnt(0)
	s_barrier
	s_add_i32 s53, s37, 0x8000
	s_cmp_lg_u32 s37, 0x18000
	s_cselect_b32 s53, s53, 0
	v_add_u32_e32 v168, s53, v165
	v_add_u32_e32 v169, s53, v164
	v_mfma_f32_16x16x32_f16 v[68:71], v[132:135], v[238:241], v[68:71]
	ds_read_b128 v[148:151], v168 offset:16
	ds_read_b128 v[184:187], v169 offset:16
	v_mfma_f32_16x16x32_f16 v[72:75], v[136:139], v[238:241], v[72:75]
	ds_read_b128 v[152:155], v168 offset:1040
	ds_read_b128 v[188:191], v169 offset:1040
	v_mfma_f32_16x16x32_f16 v[76:79], v[140:143], v[238:241], v[76:79]
	ds_read_b128 v[156:159], v168 offset:2064
	ds_read_b128 v[192:195], v169 offset:2064
	v_mfma_f32_16x16x32_f16 v[80:83], v[144:147], v[238:241], v[80:83]
	ds_read_b128 v[160:163], v168 offset:3088
	ds_read_b128 v[196:199], v169 offset:3088
	v_mfma_f32_16x16x32_f16 v[84:87], v[132:135], v[242:245], v[84:87]
	v_mfma_f32_16x16x32_f16 v[88:91], v[136:139], v[242:245], v[88:91]
	v_mfma_f32_16x16x32_f16 v[92:95], v[140:143], v[242:245], v[92:95]
	v_mfma_f32_16x16x32_f16 v[96:99], v[144:147], v[242:245], v[96:99]
	v_mfma_f32_16x16x32_f16 v[100:103], v[132:135], v[246:249], v[100:103]
	v_mfma_f32_16x16x32_f16 v[104:107], v[136:139], v[246:249], v[104:107]
	v_mfma_f32_16x16x32_f16 v[108:111], v[140:143], v[246:249], v[108:111]
	v_mfma_f32_16x16x32_f16 v[112:115], v[144:147], v[246:249], v[112:115]
	v_mfma_f32_16x16x32_f16 v[116:119], v[132:135], v[250:253], v[116:119]
	v_mfma_f32_16x16x32_f16 v[120:123], v[136:139], v[250:253], v[120:123]
	v_mfma_f32_16x16x32_f16 v[124:127], v[140:143], v[250:253], v[124:127]
	v_mfma_f32_16x16x32_f16 v[128:131], v[144:147], v[250:253], v[128:131]
	s_waitcnt lgkmcnt(0)
	s_mov_b32 s37, s53
	v_add_u32_e32 v169, s37, v164
	v_mfma_f32_16x16x32_f16 v[4:7], v[148:151], v[184:187], v[4:7]
	ds_read_b128 v[238:241], v169 offset:4112
	v_mfma_f32_16x16x32_f16 v[8:11], v[152:155], v[184:187], v[8:11]
	ds_read_b128 v[242:245], v169 offset:5136
	v_mfma_f32_16x16x32_f16 v[12:15], v[156:159], v[184:187], v[12:15]
	ds_read_b128 v[246:249], v169 offset:6160
	v_mfma_f32_16x16x32_f16 v[16:19], v[160:163], v[184:187], v[16:19]
	ds_read_b128 v[250:253], v169 offset:7184
	v_mfma_f32_16x16x32_f16 v[20:23], v[148:151], v[188:191], v[20:23]
	v_mfma_f32_16x16x32_f16 v[24:27], v[152:155], v[188:191], v[24:27]
	v_mfma_f32_16x16x32_f16 v[28:31], v[156:159], v[188:191], v[28:31]
	v_mfma_f32_16x16x32_f16 v[32:35], v[160:163], v[188:191], v[32:35]
	v_mfma_f32_16x16x32_f16 v[36:39], v[148:151], v[192:195], v[36:39]
	v_mfma_f32_16x16x32_f16 v[40:43], v[152:155], v[192:195], v[40:43]
	v_mfma_f32_16x16x32_f16 v[44:47], v[156:159], v[192:195], v[44:47]
	v_mfma_f32_16x16x32_f16 v[48:51], v[160:163], v[192:195], v[48:51]
	v_mfma_f32_16x16x32_f16 v[52:55], v[148:151], v[196:199], v[52:55]
	v_mfma_f32_16x16x32_f16 v[56:59], v[152:155], v[196:199], v[56:59]
	v_mfma_f32_16x16x32_f16 v[60:63], v[156:159], v[196:199], v[60:63]
	v_mfma_f32_16x16x32_f16 v[64:67], v[160:163], v[196:199], v[64:67]
	s_waitcnt vmcnt(4) lgkmcnt(0)
	s_barrier
	s_add_i32 s53, s37, 0x8000
	s_cmp_lg_u32 s37, 0x18000
	s_cselect_b32 s53, s53, 0
	v_add_u32_e32 v168, s53, v165
	v_add_u32_e32 v169, s53, v164
	v_mfma_f32_16x16x32_f16 v[68:71], v[148:151], v[238:241], v[68:71]
	ds_read_b128 v[132:135], v168 offset:16
	ds_read_b128 v[184:187], v169 offset:16
	v_mfma_f32_16x16x32_f16 v[72:75], v[152:155], v[238:241], v[72:75]
	ds_read_b128 v[136:139], v168 offset:1040
	ds_read_b128 v[188:191], v169 offset:1040
	v_mfma_f32_16x16x32_f16 v[76:79], v[156:159], v[238:241], v[76:79]
	ds_read_b128 v[140:143], v168 offset:2064
	ds_read_b128 v[192:195], v169 offset:2064
	v_mfma_f32_16x16x32_f16 v[80:83], v[160:163], v[238:241], v[80:83]
	ds_read_b128 v[144:147], v168 offset:3088
	ds_read_b128 v[196:199], v169 offset:3088
	v_mfma_f32_16x16x32_f16 v[84:87], v[148:151], v[242:245], v[84:87]
	v_mfma_f32_16x16x32_f16 v[88:91], v[152:155], v[242:245], v[88:91]
	v_mfma_f32_16x16x32_f16 v[92:95], v[156:159], v[242:245], v[92:95]
	v_mfma_f32_16x16x32_f16 v[96:99], v[160:163], v[242:245], v[96:99]
	v_mfma_f32_16x16x32_f16 v[100:103], v[148:151], v[246:249], v[100:103]
	v_mfma_f32_16x16x32_f16 v[104:107], v[152:155], v[246:249], v[104:107]
	v_mfma_f32_16x16x32_f16 v[108:111], v[156:159], v[246:249], v[108:111]
	v_mfma_f32_16x16x32_f16 v[112:115], v[160:163], v[246:249], v[112:115]
	v_mfma_f32_16x16x32_f16 v[116:119], v[148:151], v[250:253], v[116:119]
	v_mfma_f32_16x16x32_f16 v[120:123], v[152:155], v[250:253], v[120:123]
	v_mfma_f32_16x16x32_f16 v[124:127], v[156:159], v[250:253], v[124:127]
	v_mfma_f32_16x16x32_f16 v[128:131], v[160:163], v[250:253], v[128:131]
	s_waitcnt lgkmcnt(0)
	s_mov_b32 s37, s53
	v_add_u32_e32 v169, s37, v164
	v_mfma_f32_16x16x32_f16 v[4:7], v[132:135], v[184:187], v[4:7]
	ds_read_b128 v[238:241], v169 offset:4112
	v_mfma_f32_16x16x32_f16 v[8:11], v[136:139], v[184:187], v[8:11]
	ds_read_b128 v[242:245], v169 offset:5136
	v_mfma_f32_16x16x32_f16 v[12:15], v[140:143], v[184:187], v[12:15]
	ds_read_b128 v[246:249], v169 offset:6160
	v_mfma_f32_16x16x32_f16 v[16:19], v[144:147], v[184:187], v[16:19]
	ds_read_b128 v[250:253], v169 offset:7184
	v_mfma_f32_16x16x32_f16 v[20:23], v[132:135], v[188:191], v[20:23]
	v_mfma_f32_16x16x32_f16 v[24:27], v[136:139], v[188:191], v[24:27]
	v_mfma_f32_16x16x32_f16 v[28:31], v[140:143], v[188:191], v[28:31]
	v_mfma_f32_16x16x32_f16 v[32:35], v[144:147], v[188:191], v[32:35]
	v_mfma_f32_16x16x32_f16 v[36:39], v[132:135], v[192:195], v[36:39]
	v_mfma_f32_16x16x32_f16 v[40:43], v[136:139], v[192:195], v[40:43]
	v_mfma_f32_16x16x32_f16 v[44:47], v[140:143], v[192:195], v[44:47]
	v_mfma_f32_16x16x32_f16 v[48:51], v[144:147], v[192:195], v[48:51]
	v_mfma_f32_16x16x32_f16 v[52:55], v[132:135], v[196:199], v[52:55]
	v_mfma_f32_16x16x32_f16 v[56:59], v[136:139], v[196:199], v[56:59]
	v_mfma_f32_16x16x32_f16 v[60:63], v[140:143], v[196:199], v[60:63]
	v_mfma_f32_16x16x32_f16 v[64:67], v[144:147], v[196:199], v[64:67]
	s_waitcnt vmcnt(0) lgkmcnt(0)
	s_barrier
	s_add_i32 s53, s37, 0x8000
	s_cmp_lg_u32 s37, 0x18000
	s_cselect_b32 s53, s53, 0
	v_add_u32_e32 v168, s53, v165
	v_add_u32_e32 v169, s53, v164
	v_mfma_f32_16x16x32_f16 v[68:71], v[132:135], v[238:241], v[68:71]
	ds_read_b128 v[148:151], v168 offset:16
	ds_read_b128 v[184:187], v169 offset:16
	v_mfma_f32_16x16x32_f16 v[72:75], v[136:139], v[238:241], v[72:75]
	ds_read_b128 v[152:155], v168 offset:1040
	ds_read_b128 v[188:191], v169 offset:1040
	v_mfma_f32_16x16x32_f16 v[76:79], v[140:143], v[238:241], v[76:79]
	ds_read_b128 v[156:159], v168 offset:2064
	ds_read_b128 v[192:195], v169 offset:2064
	v_mfma_f32_16x16x32_f16 v[80:83], v[144:147], v[238:241], v[80:83]
	ds_read_b128 v[160:163], v168 offset:3088
	ds_read_b128 v[196:199], v169 offset:3088
	v_mfma_f32_16x16x32_f16 v[84:87], v[132:135], v[242:245], v[84:87]
	v_mfma_f32_16x16x32_f16 v[88:91], v[136:139], v[242:245], v[88:91]
	v_mfma_f32_16x16x32_f16 v[92:95], v[140:143], v[242:245], v[92:95]
	v_mfma_f32_16x16x32_f16 v[96:99], v[144:147], v[242:245], v[96:99]
	v_mfma_f32_16x16x32_f16 v[100:103], v[132:135], v[246:249], v[100:103]
	v_mfma_f32_16x16x32_f16 v[104:107], v[136:139], v[246:249], v[104:107]
	v_mfma_f32_16x16x32_f16 v[108:111], v[140:143], v[246:249], v[108:111]
	v_mfma_f32_16x16x32_f16 v[112:115], v[144:147], v[246:249], v[112:115]
	v_mfma_f32_16x16x32_f16 v[116:119], v[132:135], v[250:253], v[116:119]
	v_mfma_f32_16x16x32_f16 v[120:123], v[136:139], v[250:253], v[120:123]
	v_mfma_f32_16x16x32_f16 v[124:127], v[140:143], v[250:253], v[124:127]
	v_mfma_f32_16x16x32_f16 v[128:131], v[144:147], v[250:253], v[128:131]
	s_waitcnt lgkmcnt(0)
	s_mov_b32 s37, s53
	v_add_u32_e32 v169, s37, v164
	v_mfma_f32_16x16x32_f16 v[4:7], v[148:151], v[184:187], v[4:7]
	ds_read_b128 v[238:241], v169 offset:4112
	v_mfma_f32_16x16x32_f16 v[8:11], v[152:155], v[184:187], v[8:11]
	ds_read_b128 v[242:245], v169 offset:5136
	v_mfma_f32_16x16x32_f16 v[12:15], v[156:159], v[184:187], v[12:15]
	ds_read_b128 v[246:249], v169 offset:6160
	v_mfma_f32_16x16x32_f16 v[16:19], v[160:163], v[184:187], v[16:19]
	ds_read_b128 v[250:253], v169 offset:7184
	v_mfma_f32_16x16x32_f16 v[20:23], v[148:151], v[188:191], v[20:23]
	v_mfma_f32_16x16x32_f16 v[24:27], v[152:155], v[188:191], v[24:27]
	v_mfma_f32_16x16x32_f16 v[28:31], v[156:159], v[188:191], v[28:31]
	v_mfma_f32_16x16x32_f16 v[32:35], v[160:163], v[188:191], v[32:35]
	v_mfma_f32_16x16x32_f16 v[36:39], v[148:151], v[192:195], v[36:39]
	v_mfma_f32_16x16x32_f16 v[40:43], v[152:155], v[192:195], v[40:43]
	v_mfma_f32_16x16x32_f16 v[44:47], v[156:159], v[192:195], v[44:47]
	v_mfma_f32_16x16x32_f16 v[48:51], v[160:163], v[192:195], v[48:51]
	v_mfma_f32_16x16x32_f16 v[52:55], v[148:151], v[196:199], v[52:55]
	v_mfma_f32_16x16x32_f16 v[56:59], v[152:155], v[196:199], v[56:59]
	v_mfma_f32_16x16x32_f16 v[60:63], v[156:159], v[196:199], v[60:63]
	v_mfma_f32_16x16x32_f16 v[64:67], v[160:163], v[196:199], v[64:67]
	s_waitcnt lgkmcnt(0)
	s_barrier
	v_mfma_f32_16x16x32_f16 v[68:71], v[148:151], v[238:241], v[68:71]
	v_mfma_f32_16x16x32_f16 v[72:75], v[152:155], v[238:241], v[72:75]
	v_mfma_f32_16x16x32_f16 v[76:79], v[156:159], v[238:241], v[76:79]
	v_mfma_f32_16x16x32_f16 v[80:83], v[160:163], v[238:241], v[80:83]
	v_mfma_f32_16x16x32_f16 v[84:87], v[148:151], v[242:245], v[84:87]
	v_mfma_f32_16x16x32_f16 v[88:91], v[152:155], v[242:245], v[88:91]
	v_mfma_f32_16x16x32_f16 v[92:95], v[156:159], v[242:245], v[92:95]
	v_mfma_f32_16x16x32_f16 v[96:99], v[160:163], v[242:245], v[96:99]
	v_mfma_f32_16x16x32_f16 v[100:103], v[148:151], v[246:249], v[100:103]
	v_mfma_f32_16x16x32_f16 v[104:107], v[152:155], v[246:249], v[104:107]
	v_mfma_f32_16x16x32_f16 v[108:111], v[156:159], v[246:249], v[108:111]
	v_mfma_f32_16x16x32_f16 v[112:115], v[160:163], v[246:249], v[112:115]
	v_mfma_f32_16x16x32_f16 v[116:119], v[148:151], v[250:253], v[116:119]
	v_mfma_f32_16x16x32_f16 v[120:123], v[152:155], v[250:253], v[120:123]
	v_mfma_f32_16x16x32_f16 v[124:127], v[156:159], v[250:253], v[124:127]
	v_mfma_f32_16x16x32_f16 v[128:131], v[160:163], v[250:253], v[128:131]
	s_add_i32 s55, s54, s76
	s_cmp_ge_i32 s55, s58
	s_cbranch_scc1 .Lnopf_mlp1a
	s_lshr_b32 s77, s55, 4
	s_lshl_b32 s82, s77, 3
	s_or_b32 s82, s82, s83
	s_and_b64 s[80:81], s[74:75], exec
	s_cselect_b32 s37, s82, s77
	s_lshl_b32 s82, s77, 4
	s_sub_i32 s53, s55, s82
	s_lshl_b32 s53, s53, 8
	s_lshl_b32 s82, s37, 19
	s_add_u32 s68, s42, s82
	s_addc_u32 s69, s43, 0
	s_lshl_b32 s82, s53, 11
	s_add_u32 s80, s44, s82
	s_addc_u32 s81, s45, 0
	s_sub_u32 s82, s32, 16
	s_lshl_b32 s82, s82, 5
	s_add_u32 s68, s68, s82
	s_addc_u32 s69, s69, 0
	s_add_u32 s80, s80, s82
	s_addc_u32 s81, s81, 0
	v_bfe_u32 v172, v200, 6, 2
	v_bfe_u32 v173, v200, 4, 2
	v_lshlrev_b32_e32 v172, 6, v172
	v_lshl_or_b32 v172, v173, 2, v172
	v_add_u32_e32 v172, s53, v172
	v_lshlrev_b32_e32 v172, 2, v172
	global_load_dwordx4 v[132:135], v172, s[24:25]
	global_load_dwordx4 v[136:139], v172, s[24:25] offset:64
	global_load_dwordx4 v[140:143], v172, s[24:25] offset:128
	global_load_dwordx4 v[144:147], v172, s[24:25] offset:192
	s_mov_b32 s82, s32
	s_mov_b32 m0, s82
	s_nop 0
	global_load_lds_dwordx4 v170, s[68:69]
	s_add_u32 m0, s82, 0x400
	s_nop 0
	global_load_lds_dwordx4 v171, s[68:69]
	s_add_u32 m0, s82, 0x4000
	s_nop 0
	global_load_lds_dwordx4 v170, s[80:81]
	s_add_u32 m0, s82, 0x4400
	s_nop 0
	global_load_lds_dwordx4 v171, s[80:81]
	s_add_u32 s68, s68, 64
	s_addc_u32 s69, s69, 0
	s_add_u32 s80, s80, 64
	s_addc_u32 s81, s81, 0
	s_add_u32 s82, s32, 0x8000
	s_mov_b32 m0, s82
	s_nop 0
	global_load_lds_dwordx4 v170, s[68:69]
	s_add_u32 m0, s82, 0x400
	s_nop 0
	global_load_lds_dwordx4 v171, s[68:69]
	s_add_u32 m0, s82, 0x4000
	s_nop 0
	global_load_lds_dwordx4 v170, s[80:81]
	s_add_u32 m0, s82, 0x4400
	s_nop 0
	global_load_lds_dwordx4 v171, s[80:81]
	s_add_u32 s68, s68, 64
	s_addc_u32 s69, s69, 0
	s_add_u32 s80, s80, 64
	s_addc_u32 s81, s81, 0
	s_add_u32 s82, s32, 0x10000
	s_mov_b32 m0, s82
	s_nop 0
	global_load_lds_dwordx4 v170, s[68:69]
	s_add_u32 m0, s82, 0x400
	s_nop 0
	global_load_lds_dwordx4 v171, s[68:69]
	s_add_u32 m0, s82, 0x4000
	s_nop 0
	global_load_lds_dwordx4 v170, s[80:81]
	s_add_u32 m0, s82, 0x4400
	s_nop 0
	global_load_lds_dwordx4 v171, s[80:81]
	s_add_u32 s68, s68, 64
	s_addc_u32 s69, s69, 0
	s_add_u32 s80, s80, 64
	s_addc_u32 s81, s81, 0
	s_add_u32 s82, s32, 0x18000
	s_mov_b32 m0, s82
	s_nop 0
	global_load_lds_dwordx4 v170, s[68:69]
	s_add_u32 m0, s82, 0x400
	s_nop 0
	global_load_lds_dwordx4 v171, s[68:69]
	s_add_u32 m0, s82, 0x4000
	s_nop 0
	global_load_lds_dwordx4 v170, s[80:81]
	s_add_u32 m0, s82, 0x4400
	s_nop 0
	global_load_lds_dwordx4 v171, s[80:81]
	s_add_u32 s68, s68, 64
	s_addc_u32 s69, s69, 0
	s_add_u32 s80, s80, 64
	s_addc_u32 s81, s81, 0
.Lnopf_mlp1a:
	s_lshl_b64 s[80:81], s[28:29], 13
	s_add_u32 s80, s80, s34
	s_addc_u32 s81, s81, s35
	s_lshl_b32 s82, s65, 1
	s_add_u32 s80, s80, s82
	s_addc_u32 s81, s81, 0
	v_and_b32_e32 v172, 15, v200
	v_bfe_u32 v173, v200, 4, 2
	v_bfe_u32 v174, v200, 6, 2
	v_bfe_u32 v175, v200, 8, 1
	v_lshl_or_b32 v175, v175, 7, v172
	v_lshlrev_b32_e32 v175, 13, v175
	v_lshlrev_b32_e32 v174, 6, v174
	v_lshl_or_b32 v174, v173, 2, v174
	v_lshl_add_u32 v177, v174, 1, v175
	v_and_b32_e32 v172, 1, v173
	v_mul_u32_u24_e32 v172, 24, v172
	v_add_u32_e32 v177, v177, v172
	v_max_f32_e32 v4, 0, v4
	v_max_f32_e32 v5, 0, v5
	v_max_f32_e32 v6, 0, v6
	v_max_f32_e32 v7, 0, v7
	v_pk_mul_f32 v[4:5], v[4:5], v[4:5]
	v_pk_mul_f32 v[6:7], v[6:7], v[6:7]
	v_cvt_pk_f16_f32 v172, v4, v5
	v_cvt_pk_f16_f32 v173, v6, v7
	v_max_f32_e32 v8, 0, v8
	v_max_f32_e32 v9, 0, v9
	v_max_f32_e32 v10, 0, v10
	v_max_f32_e32 v11, 0, v11
	v_pk_mul_f32 v[8:9], v[8:9], v[8:9]
	v_pk_mul_f32 v[10:11], v[10:11], v[10:11]
	v_cvt_pk_f16_f32 v174, v8, v9
	v_cvt_pk_f16_f32 v175, v10, v11
	s_nop 1
	v_permlane16_swap_b32_e32 v172, v174
	v_permlane16_swap_b32_e32 v173, v175
	global_store_dwordx4 v177, v[172:175], s[80:81]
	v_max_f32_e32 v12, 0, v12
	v_max_f32_e32 v13, 0, v13
	v_max_f32_e32 v14, 0, v14
	v_max_f32_e32 v15, 0, v15
	v_pk_mul_f32 v[12:13], v[12:13], v[12:13]
	v_pk_mul_f32 v[14:15], v[14:15], v[14:15]
	v_cvt_pk_f16_f32 v228, v12, v13
	v_cvt_pk_f16_f32 v229, v14, v15
	v_max_f32_e32 v16, 0, v16
	v_max_f32_e32 v17, 0, v17
	v_max_f32_e32 v18, 0, v18
	v_max_f32_e32 v19, 0, v19
	v_pk_mul_f32 v[16:17], v[16:17], v[16:17]
	v_pk_mul_f32 v[18:19], v[18:19], v[18:19]
	v_cvt_pk_f16_f32 v230, v16, v17
	v_cvt_pk_f16_f32 v231, v18, v19
	s_nop 1
	v_permlane16_swap_b32_e32 v228, v230
	v_permlane16_swap_b32_e32 v229, v231
	global_store_dwordx4 v177, v[228:231], s[80:81] offset:64
	v_add_u32_e32 v177, 0x20000, v177
	v_max_f32_e32 v20, 0, v20
	v_max_f32_e32 v21, 0, v21
	v_max_f32_e32 v22, 0, v22
	v_max_f32_e32 v23, 0, v23
	v_pk_mul_f32 v[20:21], v[20:21], v[20:21]
	v_pk_mul_f32 v[22:23], v[22:23], v[22:23]
	v_cvt_pk_f16_f32 v172, v20, v21
	v_cvt_pk_f16_f32 v173, v22, v23
	v_max_f32_e32 v24, 0, v24
	v_max_f32_e32 v25, 0, v25
	v_max_f32_e32 v26, 0, v26
	v_max_f32_e32 v27, 0, v27
	v_pk_mul_f32 v[24:25], v[24:25], v[24:25]
	v_pk_mul_f32 v[26:27], v[26:27], v[26:27]
	v_cvt_pk_f16_f32 v174, v24, v25
	v_cvt_pk_f16_f32 v175, v26, v27
	s_nop 1
	v_permlane16_swap_b32_e32 v172, v174
	v_permlane16_swap_b32_e32 v173, v175
	global_store_dwordx4 v177, v[172:175], s[80:81]
	v_max_f32_e32 v28, 0, v28
	v_max_f32_e32 v29, 0, v29
	v_max_f32_e32 v30, 0, v30
	v_max_f32_e32 v31, 0, v31
	v_pk_mul_f32 v[28:29], v[28:29], v[28:29]
	v_pk_mul_f32 v[30:31], v[30:31], v[30:31]
	v_cvt_pk_f16_f32 v228, v28, v29
	v_cvt_pk_f16_f32 v229, v30, v31
	v_max_f32_e32 v32, 0, v32
	v_max_f32_e32 v33, 0, v33
	v_max_f32_e32 v34, 0, v34
	v_max_f32_e32 v35, 0, v35
	v_pk_mul_f32 v[32:33], v[32:33], v[32:33]
	v_pk_mul_f32 v[34:35], v[34:35], v[34:35]
	v_cvt_pk_f16_f32 v230, v32, v33
	v_cvt_pk_f16_f32 v231, v34, v35
	s_nop 1
	v_permlane16_swap_b32_e32 v228, v230
	v_permlane16_swap_b32_e32 v229, v231
	global_store_dwordx4 v177, v[228:231], s[80:81] offset:64
	v_add_u32_e32 v177, 0x20000, v177
	v_max_f32_e32 v36, 0, v36
	v_max_f32_e32 v37, 0, v37
	v_max_f32_e32 v38, 0, v38
	v_max_f32_e32 v39, 0, v39
	v_pk_mul_f32 v[36:37], v[36:37], v[36:37]
	v_pk_mul_f32 v[38:39], v[38:39], v[38:39]
	v_cvt_pk_f16_f32 v172, v36, v37
	v_cvt_pk_f16_f32 v173, v38, v39
	v_max_f32_e32 v40, 0, v40
	v_max_f32_e32 v41, 0, v41
	v_max_f32_e32 v42, 0, v42
	v_max_f32_e32 v43, 0, v43
	v_pk_mul_f32 v[40:41], v[40:41], v[40:41]
	v_pk_mul_f32 v[42:43], v[42:43], v[42:43]
	v_cvt_pk_f16_f32 v174, v40, v41
	v_cvt_pk_f16_f32 v175, v42, v43
	s_nop 1
	v_permlane16_swap_b32_e32 v172, v174
	v_permlane16_swap_b32_e32 v173, v175
	global_store_dwordx4 v177, v[172:175], s[80:81]
	v_max_f32_e32 v44, 0, v44
	v_max_f32_e32 v45, 0, v45
	v_max_f32_e32 v46, 0, v46
	v_max_f32_e32 v47, 0, v47
	v_pk_mul_f32 v[44:45], v[44:45], v[44:45]
	v_pk_mul_f32 v[46:47], v[46:47], v[46:47]
	v_cvt_pk_f16_f32 v228, v44, v45
	v_cvt_pk_f16_f32 v229, v46, v47
	v_max_f32_e32 v48, 0, v48
	v_max_f32_e32 v49, 0, v49
	v_max_f32_e32 v50, 0, v50
	v_max_f32_e32 v51, 0, v51
	v_pk_mul_f32 v[48:49], v[48:49], v[48:49]
	v_pk_mul_f32 v[50:51], v[50:51], v[50:51]
	v_cvt_pk_f16_f32 v230, v48, v49
	v_cvt_pk_f16_f32 v231, v50, v51
	s_nop 1
	v_permlane16_swap_b32_e32 v228, v230
	v_permlane16_swap_b32_e32 v229, v231
	global_store_dwordx4 v177, v[228:231], s[80:81] offset:64
	v_add_u32_e32 v177, 0x20000, v177
	v_max_f32_e32 v52, 0, v52
	v_max_f32_e32 v53, 0, v53
	v_max_f32_e32 v54, 0, v54
	v_max_f32_e32 v55, 0, v55
	v_pk_mul_f32 v[52:53], v[52:53], v[52:53]
	v_pk_mul_f32 v[54:55], v[54:55], v[54:55]
	v_cvt_pk_f16_f32 v172, v52, v53
	v_cvt_pk_f16_f32 v173, v54, v55
	v_max_f32_e32 v56, 0, v56
	v_max_f32_e32 v57, 0, v57
	v_max_f32_e32 v58, 0, v58
	v_max_f32_e32 v59, 0, v59
	v_pk_mul_f32 v[56:57], v[56:57], v[56:57]
	v_pk_mul_f32 v[58:59], v[58:59], v[58:59]
	v_cvt_pk_f16_f32 v174, v56, v57
	v_cvt_pk_f16_f32 v175, v58, v59
	s_nop 1
	v_permlane16_swap_b32_e32 v172, v174
	v_permlane16_swap_b32_e32 v173, v175
	global_store_dwordx4 v177, v[172:175], s[80:81]
	v_max_f32_e32 v60, 0, v60
	v_max_f32_e32 v61, 0, v61
	v_max_f32_e32 v62, 0, v62
	v_max_f32_e32 v63, 0, v63
	v_pk_mul_f32 v[60:61], v[60:61], v[60:61]
	v_pk_mul_f32 v[62:63], v[62:63], v[62:63]
	v_cvt_pk_f16_f32 v228, v60, v61
	v_cvt_pk_f16_f32 v229, v62, v63
	v_max_f32_e32 v64, 0, v64
	v_max_f32_e32 v65, 0, v65
	v_max_f32_e32 v66, 0, v66
	v_max_f32_e32 v67, 0, v67
	v_pk_mul_f32 v[64:65], v[64:65], v[64:65]
	v_pk_mul_f32 v[66:67], v[66:67], v[66:67]
	v_cvt_pk_f16_f32 v230, v64, v65
	v_cvt_pk_f16_f32 v231, v66, v67
	s_nop 1
	v_permlane16_swap_b32_e32 v228, v230
	v_permlane16_swap_b32_e32 v229, v231
	global_store_dwordx4 v177, v[228:231], s[80:81] offset:64
	v_add_u32_e32 v177, 0x20000, v177
	v_max_f32_e32 v68, 0, v68
	v_max_f32_e32 v69, 0, v69
	v_max_f32_e32 v70, 0, v70
	v_max_f32_e32 v71, 0, v71
	v_pk_mul_f32 v[68:69], v[68:69], v[68:69]
	v_pk_mul_f32 v[70:71], v[70:71], v[70:71]
	v_cvt_pk_f16_f32 v172, v68, v69
	v_cvt_pk_f16_f32 v173, v70, v71
	v_max_f32_e32 v72, 0, v72
	v_max_f32_e32 v73, 0, v73
	v_max_f32_e32 v74, 0, v74
	v_max_f32_e32 v75, 0, v75
	v_pk_mul_f32 v[72:73], v[72:73], v[72:73]
	v_pk_mul_f32 v[74:75], v[74:75], v[74:75]
	v_cvt_pk_f16_f32 v174, v72, v73
	v_cvt_pk_f16_f32 v175, v74, v75
	s_nop 1
	v_permlane16_swap_b32_e32 v172, v174
	v_permlane16_swap_b32_e32 v173, v175
	global_store_dwordx4 v177, v[172:175], s[80:81]
	v_max_f32_e32 v76, 0, v76
	v_max_f32_e32 v77, 0, v77
	v_max_f32_e32 v78, 0, v78
	v_max_f32_e32 v79, 0, v79
	v_pk_mul_f32 v[76:77], v[76:77], v[76:77]
	v_pk_mul_f32 v[78:79], v[78:79], v[78:79]
	v_cvt_pk_f16_f32 v228, v76, v77
	v_cvt_pk_f16_f32 v229, v78, v79
	v_max_f32_e32 v80, 0, v80
	v_max_f32_e32 v81, 0, v81
	v_max_f32_e32 v82, 0, v82
	v_max_f32_e32 v83, 0, v83
	v_pk_mul_f32 v[80:81], v[80:81], v[80:81]
	v_pk_mul_f32 v[82:83], v[82:83], v[82:83]
	v_cvt_pk_f16_f32 v230, v80, v81
	v_cvt_pk_f16_f32 v231, v82, v83
	s_nop 1
	v_permlane16_swap_b32_e32 v228, v230
	v_permlane16_swap_b32_e32 v229, v231
	global_store_dwordx4 v177, v[228:231], s[80:81] offset:64
	v_add_u32_e32 v177, 0x20000, v177
	v_max_f32_e32 v84, 0, v84
	v_max_f32_e32 v85, 0, v85
	v_max_f32_e32 v86, 0, v86
	v_max_f32_e32 v87, 0, v87
	v_pk_mul_f32 v[84:85], v[84:85], v[84:85]
	v_pk_mul_f32 v[86:87], v[86:87], v[86:87]
	v_cvt_pk_f16_f32 v172, v84, v85
	v_cvt_pk_f16_f32 v173, v86, v87
	v_max_f32_e32 v88, 0, v88
	v_max_f32_e32 v89, 0, v89
	v_max_f32_e32 v90, 0, v90
	v_max_f32_e32 v91, 0, v91
	v_pk_mul_f32 v[88:89], v[88:89], v[88:89]
	v_pk_mul_f32 v[90:91], v[90:91], v[90:91]
	v_cvt_pk_f16_f32 v174, v88, v89
	v_cvt_pk_f16_f32 v175, v90, v91
	s_nop 1
	v_permlane16_swap_b32_e32 v172, v174
	v_permlane16_swap_b32_e32 v173, v175
	global_store_dwordx4 v177, v[172:175], s[80:81]
	v_max_f32_e32 v92, 0, v92
	v_max_f32_e32 v93, 0, v93
	v_max_f32_e32 v94, 0, v94
	v_max_f32_e32 v95, 0, v95
	v_pk_mul_f32 v[92:93], v[92:93], v[92:93]
	v_pk_mul_f32 v[94:95], v[94:95], v[94:95]
	v_cvt_pk_f16_f32 v228, v92, v93
	v_cvt_pk_f16_f32 v229, v94, v95
	v_max_f32_e32 v96, 0, v96
	v_max_f32_e32 v97, 0, v97
	v_max_f32_e32 v98, 0, v98
	v_max_f32_e32 v99, 0, v99
	v_pk_mul_f32 v[96:97], v[96:97], v[96:97]
	v_pk_mul_f32 v[98:99], v[98:99], v[98:99]
	v_cvt_pk_f16_f32 v230, v96, v97
	v_cvt_pk_f16_f32 v231, v98, v99
	s_nop 1
	v_permlane16_swap_b32_e32 v228, v230
	v_permlane16_swap_b32_e32 v229, v231
	global_store_dwordx4 v177, v[228:231], s[80:81] offset:64
	v_add_u32_e32 v177, 0x20000, v177
	v_max_f32_e32 v100, 0, v100
	v_max_f32_e32 v101, 0, v101
	v_max_f32_e32 v102, 0, v102
	v_max_f32_e32 v103, 0, v103
	v_pk_mul_f32 v[100:101], v[100:101], v[100:101]
	v_pk_mul_f32 v[102:103], v[102:103], v[102:103]
	v_cvt_pk_f16_f32 v172, v100, v101
	v_cvt_pk_f16_f32 v173, v102, v103
	v_max_f32_e32 v104, 0, v104
	v_max_f32_e32 v105, 0, v105
	v_max_f32_e32 v106, 0, v106
	v_max_f32_e32 v107, 0, v107
	v_pk_mul_f32 v[104:105], v[104:105], v[104:105]
	v_pk_mul_f32 v[106:107], v[106:107], v[106:107]
	v_cvt_pk_f16_f32 v174, v104, v105
	v_cvt_pk_f16_f32 v175, v106, v107
	s_nop 1
	v_permlane16_swap_b32_e32 v172, v174
	v_permlane16_swap_b32_e32 v173, v175
	global_store_dwordx4 v177, v[172:175], s[80:81]
	v_max_f32_e32 v108, 0, v108
	v_max_f32_e32 v109, 0, v109
	v_max_f32_e32 v110, 0, v110
	v_max_f32_e32 v111, 0, v111
	v_pk_mul_f32 v[108:109], v[108:109], v[108:109]
	v_pk_mul_f32 v[110:111], v[110:111], v[110:111]
	v_cvt_pk_f16_f32 v228, v108, v109
	v_cvt_pk_f16_f32 v229, v110, v111
	v_max_f32_e32 v112, 0, v112
	v_max_f32_e32 v113, 0, v113
	v_max_f32_e32 v114, 0, v114
	v_max_f32_e32 v115, 0, v115
	v_pk_mul_f32 v[112:113], v[112:113], v[112:113]
	v_pk_mul_f32 v[114:115], v[114:115], v[114:115]
	v_cvt_pk_f16_f32 v230, v112, v113
	v_cvt_pk_f16_f32 v231, v114, v115
	s_nop 1
	v_permlane16_swap_b32_e32 v228, v230
	v_permlane16_swap_b32_e32 v229, v231
	global_store_dwordx4 v177, v[228:231], s[80:81] offset:64
	v_add_u32_e32 v177, 0x20000, v177
	v_max_f32_e32 v116, 0, v116
	v_max_f32_e32 v117, 0, v117
	v_max_f32_e32 v118, 0, v118
	v_max_f32_e32 v119, 0, v119
	v_pk_mul_f32 v[116:117], v[116:117], v[116:117]
	v_pk_mul_f32 v[118:119], v[118:119], v[118:119]
	v_cvt_pk_f16_f32 v172, v116, v117
	v_cvt_pk_f16_f32 v173, v118, v119
	v_max_f32_e32 v120, 0, v120
	v_max_f32_e32 v121, 0, v121
	v_max_f32_e32 v122, 0, v122
	v_max_f32_e32 v123, 0, v123
	v_pk_mul_f32 v[120:121], v[120:121], v[120:121]
	v_pk_mul_f32 v[122:123], v[122:123], v[122:123]
	v_cvt_pk_f16_f32 v174, v120, v121
	v_cvt_pk_f16_f32 v175, v122, v123
	s_nop 1
	v_permlane16_swap_b32_e32 v172, v174
	v_permlane16_swap_b32_e32 v173, v175
	global_store_dwordx4 v177, v[172:175], s[80:81]
	v_max_f32_e32 v124, 0, v124
	v_max_f32_e32 v125, 0, v125
	v_max_f32_e32 v126, 0, v126
	v_max_f32_e32 v127, 0, v127
	v_pk_mul_f32 v[124:125], v[124:125], v[124:125]
	v_pk_mul_f32 v[126:127], v[126:127], v[126:127]
	v_cvt_pk_f16_f32 v228, v124, v125
	v_cvt_pk_f16_f32 v229, v126, v127
	v_max_f32_e32 v128, 0, v128
	v_max_f32_e32 v129, 0, v129
	v_max_f32_e32 v130, 0, v130
	v_max_f32_e32 v131, 0, v131
	v_pk_mul_f32 v[128:129], v[128:129], v[128:129]
	v_pk_mul_f32 v[130:131], v[130:131], v[130:131]
	v_cvt_pk_f16_f32 v230, v128, v129
	v_cvt_pk_f16_f32 v231, v130, v131
	s_nop 1
	v_permlane16_swap_b32_e32 v228, v230
	v_permlane16_swap_b32_e32 v229, v231
	global_store_dwordx4 v177, v[228:231], s[80:81] offset:64
	s_nop 1
	s_cmp_ge_i32 s55, s58
	s_cbranch_scc1 .LBB0_780
	s_mov_b32 s54, s55
	s_ashr_i32 s28, s54, 31
	s_lshr_b32 s28, s28, 28
	s_add_i32 s28, s54, s28
	s_ashr_i32 s52, s28, 4
	s_lshl_b32 s28, s52, 3
	s_or_b32 s30, s28, s83
	s_and_b64 s[28:29], s[74:75], exec
	s_cselect_b32 s28, s30, s52
	s_lshl_b32 s36, s28, 8
	s_cmp_gt_i32 s28, 39
	s_mov_b64 s[30:31], -1
	s_cbranch_scc0 .Lpfh_mlp1a_727
	s_add_i32 s90, s36, 0xffffd800
	s_mov_b64 s[30:31], 0
	s_mov_b64 s[28:29], s[90:91]

.Lpfh_mlp1a_729:
	s_lshl_b32 s65, s52, 4
	s_sub_i32 s65, s54, s65
	s_lshl_b32 s65, s65, 8
	s_lshl_b32 vcc_hi, s36, 11
	s_add_u32 s30, s42, vcc_hi
	s_addc_u32 s31, s43, 0
	s_lshl_b32 vcc_hi, s65, 11
	s_add_u32 s56, s44, vcc_hi
	s_addc_u32 s57, s45, 0
	s_waitcnt lgkmcnt(0)
	v_readfirstlane_b32 vcc_hi, v200
	s_lshr_b32 vcc_hi, vcc_hi, 6
	s_lshl_b32 s32, vcc_hi, 11
	s_add_u32 s32, s32, 16
	s_lshl_b32 vcc_hi, vcc_hi, 16
	s_add_u32 s30, s30, vcc_hi
	s_addc_u32 s31, s31, 0
	s_add_u32 s56, s56, vcc_hi
	s_addc_u32 s57, s57, 0
	s_add_u32 s30, s30, 256
	s_addc_u32 s31, s31, 0
	s_add_u32 s56, s56, 256
	s_addc_u32 s57, s57, 0
	s_waitcnt vmcnt(16)
	v_mov_b32_e32 v4, v132
	v_mov_b32_e32 v5, v133
	v_mov_b32_e32 v6, v134
	v_mov_b32_e32 v7, v135
	v_mov_b32_e32 v8, v136
	v_mov_b32_e32 v9, v137
	v_mov_b32_e32 v10, v138
	v_mov_b32_e32 v11, v139
	v_mov_b32_e32 v12, v140
	v_mov_b32_e32 v13, v141
	v_mov_b32_e32 v14, v142
	v_mov_b32_e32 v15, v143
	v_mov_b32_e32 v16, v144
	v_mov_b32_e32 v17, v145
	v_mov_b32_e32 v18, v146
	v_mov_b32_e32 v19, v147
	v_mov_b32_e32 v20, v132
	v_mov_b32_e32 v21, v133
	v_mov_b32_e32 v22, v134
	v_mov_b32_e32 v23, v135
	v_mov_b32_e32 v24, v136
	v_mov_b32_e32 v25, v137
	v_mov_b32_e32 v26, v138
	v_mov_b32_e32 v27, v139
	v_mov_b32_e32 v28, v140
	v_mov_b32_e32 v29, v141
	v_mov_b32_e32 v30, v142
	v_mov_b32_e32 v31, v143
	v_mov_b32_e32 v32, v144
	v_mov_b32_e32 v33, v145
	v_mov_b32_e32 v34, v146
	v_mov_b32_e32 v35, v147
	v_mov_b32_e32 v36, v132
	v_mov_b32_e32 v37, v133
	v_mov_b32_e32 v38, v134
	v_mov_b32_e32 v39, v135
	v_mov_b32_e32 v40, v136
	v_mov_b32_e32 v41, v137
	v_mov_b32_e32 v42, v138
	v_mov_b32_e32 v43, v139
	v_mov_b32_e32 v44, v140
	v_mov_b32_e32 v45, v141
	v_mov_b32_e32 v46, v142
	v_mov_b32_e32 v47, v143
	v_mov_b32_e32 v48, v144
	v_mov_b32_e32 v49, v145
	v_mov_b32_e32 v50, v146
	v_mov_b32_e32 v51, v147
	v_mov_b32_e32 v52, v132
	v_mov_b32_e32 v53, v133
	v_mov_b32_e32 v54, v134
	v_mov_b32_e32 v55, v135
	v_mov_b32_e32 v56, v136
	v_mov_b32_e32 v57, v137
	v_mov_b32_e32 v58, v138
	v_mov_b32_e32 v59, v139
	v_mov_b32_e32 v60, v140
	v_mov_b32_e32 v61, v141
	v_mov_b32_e32 v62, v142
	v_mov_b32_e32 v63, v143
	v_mov_b32_e32 v64, v144
	v_mov_b32_e32 v65, v145
	v_mov_b32_e32 v66, v146
	v_mov_b32_e32 v67, v147
	v_mov_b32_e32 v68, v132
	v_mov_b32_e32 v69, v133
	v_mov_b32_e32 v70, v134
	v_mov_b32_e32 v71, v135
	v_mov_b32_e32 v72, v136
	v_mov_b32_e32 v73, v137
	v_mov_b32_e32 v74, v138
	v_mov_b32_e32 v75, v139
	v_mov_b32_e32 v76, v140
	v_mov_b32_e32 v77, v141
	v_mov_b32_e32 v78, v142
	v_mov_b32_e32 v79, v143
	v_mov_b32_e32 v80, v144
	v_mov_b32_e32 v81, v145
	v_mov_b32_e32 v82, v146
	v_mov_b32_e32 v83, v147
	v_mov_b32_e32 v84, v132
	v_mov_b32_e32 v85, v133
	v_mov_b32_e32 v86, v134
	v_mov_b32_e32 v87, v135
	v_mov_b32_e32 v88, v136
	v_mov_b32_e32 v89, v137
	v_mov_b32_e32 v90, v138
	v_mov_b32_e32 v91, v139
	v_mov_b32_e32 v92, v140
	v_mov_b32_e32 v93, v141
	v_mov_b32_e32 v94, v142
	v_mov_b32_e32 v95, v143
	v_mov_b32_e32 v96, v144
	v_mov_b32_e32 v97, v145
	v_mov_b32_e32 v98, v146
	v_mov_b32_e32 v99, v147
	v_mov_b32_e32 v100, v132
	v_mov_b32_e32 v101, v133
	v_mov_b32_e32 v102, v134
	v_mov_b32_e32 v103, v135
	v_mov_b32_e32 v104, v136
	v_mov_b32_e32 v105, v137
	v_mov_b32_e32 v106, v138
	v_mov_b32_e32 v107, v139
	v_mov_b32_e32 v108, v140
	v_mov_b32_e32 v109, v141
	v_mov_b32_e32 v110, v142
	v_mov_b32_e32 v111, v143
	v_mov_b32_e32 v112, v144
	v_mov_b32_e32 v113, v145
	v_mov_b32_e32 v114, v146
	v_mov_b32_e32 v115, v147
	v_mov_b32_e32 v116, v132
	v_mov_b32_e32 v117, v133
	v_mov_b32_e32 v118, v134
	v_mov_b32_e32 v119, v135
	v_mov_b32_e32 v120, v136
	v_mov_b32_e32 v121, v137
	v_mov_b32_e32 v122, v138
	v_mov_b32_e32 v123, v139
	v_mov_b32_e32 v124, v140
	v_mov_b32_e32 v125, v141
	v_mov_b32_e32 v126, v142
	v_mov_b32_e32 v127, v143
	v_mov_b32_e32 v128, v144
	v_mov_b32_e32 v129, v145
	v_mov_b32_e32 v130, v146
	v_mov_b32_e32 v131, v147
	s_barrier
	s_branch .Lmain_mlp1a
